# nt also on row-phase bf16 row loads (P5,P8,P12), scan image loads, P10 cache loads, P9 conversion loads
# speedup vs baseline: 1.0228x; 1.0041x over previous
.LBB0_349:
	s_or_b64 exec, exec, s[0:1]
	s_ashr_i32 s0, s2, 4
	s_ashr_i32 s1, s0, 31
	s_waitcnt vmcnt(0)
	v_lshrrev_b32_e32 v13, 3, v143
	s_lshl_b64 s[0:1], s[0:1], 23
	s_ashr_i32 s3, s2, 31
	v_lshl_or_b32 v130, v13, 12, s0
	v_mov_b32_e32 v131, s1
	v_lshl_add_u64 v[2:3], s[4:5], 0, v[130:131]
	s_mov_b32 s1, 0
	s_lshl_b32 s0, s30, 1
	s_lshl_b64 s[10:11], s[2:3], 19
	v_lshl_add_u64 v[2:3], v[2:3], 0, s[0:1]
	s_add_u32 s0, s97, s10
	s_addc_u32 s1, s33, s11
	v_mov_b32_e32 v11, 0
	s_add_u32 s4, s70, s10
	v_lshlrev_b32_e32 v134, 4, v143
	s_addc_u32 s5, s71, s11
	v_mov_b32_e32 v135, v11
	v_lshl_add_u64 v[4:5], s[4:5], 0, v[134:135]
	s_mov_b32 s4, 0xe000000
	v_and_b32_e32 v38, 7, v143
	v_add_co_u32_e32 v6, vcc, s4, v4
	v_lshlrev_b32_e32 v10, 5, v38
	s_nop 0
	v_addc_co_u32_e32 v7, vcc, 0, v5, vcc
	s_brev_b32 s4, 8
	v_lshl_add_u64 v[2:3], v[2:3], 0, v[10:11]
	v_add_co_u32_e32 v8, vcc, s4, v4
	global_load_dwordx4 v[14:17], v[2:3], off offset:16 nt
	global_load_dwordx4 v[26:29], v[2:3], off nt
	v_lshl_add_u64 v[2:3], s[0:1], 0, v[134:135]
	v_addc_co_u32_e32 v9, vcc, 0, v5, vcc
	s_movk_i32 s4, 0x2000
	v_add_co_u32_e32 v2, vcc, s4, v2
	s_mov_b32 s4, 0xe002000
	s_nop 0
	v_addc_co_u32_e32 v3, vcc, 0, v3, vcc
	global_load_dwordx4 v[18:21], v[6:7], off nt
	global_load_dwordx4 v[22:25], v[8:9], off nt
	v_add_co_u32_e32 v6, vcc, s4, v4
	s_mov_b32 s4, 0x10002000
	s_nop 0
	v_addc_co_u32_e32 v7, vcc, 0, v5, vcc
	s_lshl_b64 s[22:23], s[2:3], 15
	global_load_dwordx4 v[30:33], v[2:3], off nt
	global_load_dwordx4 v[66:69], v[6:7], off nt
	v_add_co_u32_e32 v2, vcc, s4, v4
	s_add_u32 s4, s70, s22
	s_nop 0
	v_addc_co_u32_e32 v3, vcc, 0, v5, vcc
	s_addc_u32 s5, s71, s23
	v_lshlrev_b32_e32 v4, 4, v142
	v_mov_b32_e32 v5, v11
	v_lshl_add_u64 v[6:7], s[4:5], 0, v[4:5]
	s_mov_b32 s4, 0x17200000
	s_lshl_b64 s[24:25], s[2:3], 17
	v_add_co_u32_e32 v6, vcc, s4, v6
	s_add_u32 s4, s50, s24
	s_nop 0
	v_addc_co_u32_e32 v7, vcc, 0, v7, vcc
	global_load_dwordx4 v[78:81], v[2:3], off nt
	global_load_dwordx4 v[74:77], v[6:7], off nt
	s_addc_u32 s5, s51, s25
	v_and_b32_e32 v2, 0xff0, v134
	global_load_dwordx4 v[34:37], v134, s[0:1] nt
	global_load_dwordx4 v[70:73], v2, s[4:5] nt
	v_and_b32_e32 v1, 0xf0, v134
	s_lshr_b32 s12, s12, 2
	v_and_b32_e32 v12, 15, v143
	v_add_u32_e32 v5, 0, v1
	v_and_b32_e32 v1, 0x70, v134
	s_and_b32 s12, s12, 0x3ffffff0
	v_add_u32_e32 v6, 0, v1
	v_or_b32_e32 v1, s12, v12
	s_movk_i32 s13, 0x90
	v_lshrrev_b32_e32 v133, 4, v142
	v_mul_lo_u32 v3, v1, s13
	v_add_u32_e32 v161, 0, v3
	v_lshlrev_b32_e32 v3, 2, v133
	v_or_b32_e32 v7, s12, v3
	s_add_i32 s12, 0, 0x11c00
	s_movk_i32 s13, 0x210
	v_mov_b32_e32 v8, s12
	v_or_b32_e32 v42, 32, v12
	v_mad_u32_u24 v9, v13, s13, v8
	v_add_u32_e32 v39, 0x200, v143
	v_mul_u32_u24_e32 v41, 0x110, v12
	v_mul_u32_u24_e32 v167, 0x90, v12
	v_or_b32_e32 v153, 16, v3
	v_or_b32_e32 v152, 32, v3
	v_or_b32_e32 v151, 48, v3
	v_or_b32_e32 v150, 64, v3
	v_or_b32_e32 v149, 0x50, v3
	v_or_b32_e32 v148, 0x60, v3
	v_or_b32_e32 v135, 0x70, v3
	v_mad_u32_u24 v12, v12, s13, v8
	v_mad_u32_u24 v8, v42, s13, v8
	v_or_b32_e32 v2, s24, v2
	v_mov_b32_e32 v3, s25
	s_mov_b64 s[12:13], 0x16a01000
	v_lshlrev_b32_e32 v132, 4, v38
	v_lshlrev_b32_e32 v163, 3, v133
	v_lshlrev_b32_e32 v165, 6, v38
	v_lshrrev_b32_e32 v38, 4, v143
	v_lshrrev_b32_e32 v40, 4, v39
	v_lshrrev_b32_e32 v39, 3, v39
	v_lshlrev_b32_e32 v175, 1, v152
	v_lshl_add_u64 v[136:137], v[2:3], 0, s[12:13]
	v_or_b32_e32 v2, s22, v4
	v_mov_b32_e32 v3, s23
	s_mov_b64 s[12:13], 0x17200400
	v_or_b32_e32 v140, s10, v134
	s_and_b32 s10, s2, 15
	s_movk_i32 s0, 0x100
	v_add_u32_e32 v164, 0, v163
	v_lshlrev_b32_e32 v7, 2, v7
	v_mul_u32_u24_e32 v38, 0x110, v38
	v_mul_u32_u24_e32 v13, 0x90, v13
	v_mul_u32_u24_e32 v40, 0x110, v40
	v_mul_u32_u24_e32 v39, 0x90, v39
	v_mul_u32_u24_e32 v43, 0x110, v42
	v_add_u32_e32 v44, 0, v175
	v_lshl_add_u64 v[138:139], v[2:3], 0, s[12:13]
	s_lshl_b32 s10, s10, 8
	v_mbcnt_lo_u32_b32 v2, -1, 0
	v_cmp_gt_u32_e64 s[4:5], 64, v143
	v_cmp_gt_u32_e64 s[0:1], s0, v143
	v_lshlrev_b32_e32 v162, 3, v142
	v_and_b32_e32 v166, 48, v143
	v_lshlrev_b32_e32 v168, 2, v153
	v_lshlrev_b32_e32 v169, 2, v152
	v_lshlrev_b32_e32 v170, 2, v151
	v_lshlrev_b32_e32 v171, 2, v150
	v_lshlrev_b32_e32 v172, 2, v149
	v_lshlrev_b32_e32 v173, 2, v148
	v_lshlrev_b32_e32 v174, 2, v135
	v_mov_b32_e32 v141, s11
	v_or3_b32 v144, v130, s10, v10
	v_mov_b32_e32 v145, v131
	s_mov_b32 s31, 31
	s_mov_b64 s[10:11], 0x1ae40000
	s_add_i32 s34, 0, 0x11a00
	v_mbcnt_hi_u32_b32 v177, -1, v2
	v_mov_b32_e32 v178, 0x358637bd
	s_mov_b32 s35, 0x800000
	s_mov_b32 s36, 0x12600000
	s_mov_b64 s[12:13], 0x1000
	s_mov_b64 s[22:23], 0x400
	s_mov_b64 s[24:25], 0x4000
	s_mov_b64 s[26:27], 0x40000
	v_add_u32_e32 v182, v5, v38
	v_add_u32_e32 v180, v6, v13
	v_add_u32_e32 v181, v5, v40
	v_add_u32_e32 v179, v6, v39
	v_add_u32_e32 v157, v164, v41
	v_add_u32_e32 v159, v12, v7
	v_add_u32_e32 v158, v164, v43
	v_add_u32_e32 v156, v44, v167
	v_add_u32_e32 v155, v8, v7
	v_add_u32_e32 v154, v9, v165
	v_mov_b32_e32 v10, v11
	v_mov_b32_e32 v12, v11
	v_mov_b32_e32 v13, v11
	v_mov_b32_e32 v38, v11
	v_mov_b32_e32 v39, v11
	v_mov_b32_e32 v40, v11
	v_mov_b32_e32 v41, v11
	v_mov_b32_e32 v42, v11
	v_mov_b32_e32 v43, v11
	v_mov_b32_e32 v44, v11
	v_mov_b32_e32 v45, v11
	v_mov_b32_e32 v46, v11
	v_mov_b32_e32 v47, v11
	v_mov_b32_e32 v48, v11
	v_mov_b32_e32 v49, v11
	v_mov_b32_e32 v50, v11
	v_mov_b32_e32 v51, v11
	v_mov_b32_e32 v52, v11
	v_mov_b32_e32 v53, v11
	v_mov_b32_e32 v54, v11
	v_mov_b32_e32 v55, v11
	v_mov_b32_e32 v56, v11
	v_mov_b32_e32 v57, v11
	v_mov_b32_e32 v62, v11
	v_mov_b32_e32 v63, v11
	v_mov_b32_e32 v64, v11
	v_mov_b32_e32 v65, v11
	v_mov_b32_e32 v58, v11
	v_mov_b32_e32 v59, v11
	v_mov_b32_e32 v60, v11
	v_mov_b32_e32 v61, v11

.LBB0_354:
	s_or_b64 exec, exec, s[28:29]
	v_lshl_add_u64 v[146:147], s[70:71], 0, v[144:145]
	v_add_co_u32_e32 v4, vcc, 0x1ae40000, v146
	v_lshl_add_u64 v[66:67], s[70:71], 0, v[140:141]
	s_nop 0
	v_addc_co_u32_e32 v5, vcc, 0, v147, vcc
	v_add_co_u32_e32 v18, vcc, 0xc004000, v66
	s_waitcnt lgkmcnt(0)
	s_barrier
	s_nop 0
	v_addc_co_u32_e32 v19, vcc, 0, v67, vcc
	v_add_co_u32_e32 v20, vcc, 0xe004000, v66
	v_lshl_add_u64 v[2:3], v[146:147], 0, s[10:11]
	s_nop 0
	v_addc_co_u32_e32 v21, vcc, 0, v67, vcc
	v_add_co_u32_e32 v22, vcc, 0x10004000, v66
	v_add_u32_e32 v160, 0, v162
	s_nop 0
	v_addc_co_u32_e32 v23, vcc, 0, v67, vcc
	v_add_co_u32_e32 v30, vcc, 0xc006000, v66
	global_load_dwordx4 v[6:9], v[4:5], off nt
	s_nop 0
	global_load_dwordx4 v[2:5], v[2:3], off offset:16 nt
	v_addc_co_u32_e32 v31, vcc, 0, v67, vcc
	global_load_dwordx4 v[34:37], v[18:19], off nt
	s_nop 0
	global_load_dwordx4 v[18:21], v[20:21], off nt
	s_nop 0
	global_load_dwordx4 v[22:25], v[22:23], off nt
	s_nop 0
	global_load_dwordx4 v[30:33], v[30:31], off nt
	ds_read2st64_b64 v[78:81], v160 offset0:34 offset1:35
	s_waitcnt vmcnt(6)
	ds_read2st64_b64 v[70:73], v160 offset0:36 offset1:37
	v_add_co_u32_e32 v118, vcc, 0xe006000, v66
	v_add_u32_e32 v176, v164, v167
	s_nop 0
	v_addc_co_u32_e32 v119, vcc, 0, v67, vcc
	v_add_u32_e32 v187, v161, v163
	s_waitcnt lgkmcnt(0)
	v_mov_b32_e32 v116, v70
	s_add_i32 s28, 0, 0x11800
	v_add_u32_e32 v70, 0x8800, v176
	v_add_co_u32_e32 v120, vcc, 0x10006000, v66
	v_add_u32_e32 v66, 0xd000, v187
	v_add_u32_e32 v189, s28, v166
	ds_read2_b64 v[82:85], v70 offset1:4
	v_add_u32_e32 v70, 0x9000, v176
	v_addc_co_u32_e32 v121, vcc, 0, v67, vcc
	ds_read2_b64 v[74:77], v66 offset1:4
	ds_read2_b64 v[66:69], v157 offset1:4
	v_add_u32_e32 v191, s28, v168
	ds_read_b128 v[86:89], v189
	ds_read_b128 v[90:93], v191
	ds_read2_b64 v[94:97], v70 offset0:32 offset1:36
	v_add_u32_e32 v70, 0x9800, v176
	ds_read2_b64 v[102:105], v70 offset0:64 offset1:68
	v_add_u32_e32 v190, s28, v169
	v_add_u32_e32 v70, 0xa000, v176
	v_add_u32_e32 v193, s28, v170
	ds_read_b128 v[110:113], v190
	ds_read_b128 v[122:125], v193
	ds_read2_b64 v[126:129], v70 offset0:96 offset1:100
	v_add_u32_e32 v70, 0xa800, v176
	v_add_u32_e32 v192, s28, v171
	ds_read2_b64 v[196:199], v70 offset0:128 offset1:132
	v_add_u32_e32 v70, 0xb000, v176
	v_add_u32_e32 v194, s28, v172
	ds_read_b128 v[200:203], v192
	ds_read_b128 v[204:207], v194
	ds_read2_b64 v[208:211], v70 offset0:160 offset1:164
	s_waitcnt lgkmcnt(10)
	v_pk_mul_f32 v[86:87], v[10:11], v[86:87]
	v_pk_mul_f32 v[88:89], v[12:13], v[88:89]
	v_add_u32_e32 v70, 0xb800, v176
	v_add_u32_e32 v184, s28, v173
	v_mfma_f32_16x16x32_bf16 v[98:101], v[82:85], v[74:77], v[86:89]
	s_waitcnt lgkmcnt(9)
	v_pk_mul_f32 v[82:83], v[38:39], v[90:91]
	v_pk_mul_f32 v[84:85], v[40:41], v[92:93]
	ds_read2_b64 v[90:93], v70 offset0:192 offset1:196
	v_add_u32_e32 v70, 0xc000, v176
	s_waitcnt lgkmcnt(9)
	v_mfma_f32_16x16x32_bf16 v[106:109], v[94:97], v[74:77], v[82:85]
	ds_read2_b64 v[94:97], v70 offset0:224 offset1:228
	v_add_u32_e32 v188, s28, v174
	ds_read_b128 v[212:215], v184
	s_waitcnt lgkmcnt(9)
	v_pk_mul_f32 v[82:83], v[42:43], v[110:111]
	v_pk_mul_f32 v[84:85], v[44:45], v[112:113]
	v_mov_b32_e32 v117, v71
	v_mov_b32_e32 v70, v80
	v_mfma_f32_16x16x32_bf16 v[110:113], v[102:105], v[74:77], v[82:85]
	v_mov_b32_e32 v71, v81
	v_cvt_pk_bf16_f32 v42, v42, v43
	v_cvt_pk_bf16_f32 v43, v44, v45
	s_waitcnt lgkmcnt(8)
	v_pk_mul_f32 v[82:83], v[46:47], v[122:123]
	v_pk_mul_f32 v[84:85], v[48:49], v[124:125]
	ds_read_b128 v[122:125], v188
	v_cvt_pk_bf16_f32 v44, v46, v47
	s_waitcnt lgkmcnt(8)
	v_mfma_f32_16x16x32_bf16 v[102:105], v[126:129], v[74:77], v[82:85]
	s_waitcnt lgkmcnt(1)
	v_pk_mul_f32 v[126:127], v[62:63], v[212:213]
	v_pk_mul_f32 v[128:129], v[64:65], v[214:215]
	s_waitcnt lgkmcnt(0)
	v_pk_mul_f32 v[122:123], v[58:59], v[122:123]
	v_pk_mul_f32 v[124:125], v[60:61], v[124:125]
	v_mfma_f32_16x16x32_bf16 v[90:93], v[90:93], v[74:77], v[126:129]
	v_cvt_pk_bf16_f32 v45, v48, v49
	v_mov_b32_e32 v114, v78
	v_mov_b32_e32 v115, v79
	v_mfma_f32_16x16x32_bf16 v[94:97], v[94:97], v[74:77], v[122:125]
	ds_read2_b64 v[126:129], v157 offset0:8 offset1:12
	v_pk_mul_f32 v[82:83], v[50:51], v[200:201]
	v_pk_mul_f32 v[84:85], v[52:53], v[202:203]
	v_add_u32_e32 v122, 0x1000, v157
	v_mfma_f32_16x16x32_bf16 v[46:49], v[74:77], v[70:73], 0
	ds_read2_b64 v[70:73], v122 offset0:40 offset1:44
	v_pk_mul_f32 v[86:87], v[54:55], v[204:205]
	v_pk_mul_f32 v[88:89], v[56:57], v[206:207]
	v_mfma_f32_16x16x32_bf16 v[82:85], v[196:199], v[74:77], v[82:85]
	v_cvt_pk_bf16_f32 v10, v10, v11
	v_cvt_pk_bf16_f32 v11, v12, v13
	v_cvt_pk_bf16_f32 v12, v38, v39
	v_mfma_f32_16x16x32_bf16 v[86:89], v[208:211], v[74:77], v[86:89]
	v_cvt_pk_bf16_f32 v13, v40, v41
	v_cvt_pk_bf16_f32 v62, v62, v63
	v_cvt_pk_bf16_f32 v63, v64, v65
	v_mfma_f32_16x16x32_bf16 v[78:81], v[74:77], v[114:117], 0
	v_cvt_pk_bf16_f32 v64, v58, v59
	v_cvt_pk_bf16_f32 v65, v60, v61
	v_cvt_pk_bf16_f32 v50, v50, v51
	s_waitcnt lgkmcnt(1)
	v_mfma_f32_16x16x32_bf16 v[74:77], v[42:45], v[126:129], 0
	v_cvt_pk_bf16_f32 v51, v52, v53
	v_cvt_pk_bf16_f32 v52, v54, v55
	v_cvt_pk_bf16_f32 v53, v56, v57
	s_waitcnt lgkmcnt(0)
	v_mfma_f32_16x16x32_bf16 v[38:41], v[42:45], v[70:73], 0
	ds_read2_b64 v[42:45], v157 offset0:24 offset1:28
	ds_read2_b64 v[70:73], v122 offset0:32 offset1:36
	v_add_u32_e32 v195, v161, v175
	v_add_u32_e32 v196, s34, v166
	v_mfma_f32_16x16x32_bf16 v[114:117], v[10:13], v[66:69], v[78:81]
	v_add_u32_e32 v183, 0x9000, v156
	v_add_u32_e32 v198, s34, v168
	v_add_u32_e32 v197, s34, v169
	s_waitcnt lgkmcnt(0)
	v_mfma_f32_16x16x32_bf16 v[10:13], v[10:13], v[70:73], v[46:49]
	s_nop 2
	ds_read2_b64 v[46:49], v157 offset0:16 offset1:20
	ds_read2_b64 v[58:61], v122 offset0:56 offset1:60
	global_load_dwordx4 v[66:69], v[118:119], off nt
	global_load_dwordx4 v[78:81], v[120:121], off nt
	ds_read2_b64 v[54:57], v122 offset0:48 offset1:52
	v_mfma_f32_16x16x32_bf16 v[42:45], v[62:65], v[42:45], v[74:77]
	v_add_u32_e32 v199, s34, v170
	v_cvt_pk_bf16_f32 v232, v98, v99
	v_cvt_pk_bf16_f32 v233, v100, v101
	s_waitcnt lgkmcnt(1)
	v_mfma_f32_16x16x32_bf16 v[38:41], v[62:65], v[58:61], v[38:41]
	v_lshl_add_u64 v[58:59], s[70:71], 0, v[138:139]
	v_lshl_add_u64 v[60:61], s[70:71], 0, v[136:137]
	global_load_dwordx4 v[74:77], v[58:59], off nt
	global_load_dwordx4 v[70:73], v[60:61], off nt
	v_add_u32_e32 v237, 4, v237
	global_load_dword v236, v237, s[70:71] sc1
	v_mfma_f32_16x16x32_bf16 v[46:49], v[50:53], v[46:49], v[114:117]
	v_cvt_pk_bf16_f32 v234, v106, v107
	v_cvt_pk_bf16_f32 v235, v108, v109
	v_add_u32_e32 v186, 0xa800, v156
	s_waitcnt lgkmcnt(0)
	v_mfma_f32_16x16x32_bf16 v[10:13], v[50:53], v[54:57], v[10:13]
	s_add_i32 s31, s31, -1
	s_nop 1
	v_pk_add_f32 v[44:45], v[44:45], v[48:49]
	v_pk_add_f32 v[42:43], v[42:43], v[46:47]
	ds_write_b128 v159, v[42:45]
	v_lshl_add_u64 v[136:137], v[136:137], 0, s[12:13]
	s_nop 0
	v_pk_add_f32 v[12:13], v[40:41], v[12:13]
	v_pk_add_f32 v[10:11], v[38:39], v[10:11]
	ds_write_b128 v159, v[10:13] offset:8448
	ds_read2st64_b64 v[10:13], v160 offset0:38 offset1:39
	ds_read2st64_b64 v[54:57], v160 offset0:40 offset1:41
	v_add_u32_e32 v38, 0xd000, v195
	ds_read2_b64 v[58:61], v38 offset1:4
	ds_read2_b64 v[50:53], v158 offset1:4
	ds_read2_b64 v[118:121], v158 offset0:8 offset1:12
	ds_read2_b64 v[46:49], v158 offset0:16 offset1:20
	ds_read2_b64 v[114:117], v158 offset0:24 offset1:28
	s_waitcnt lgkmcnt(6)
	v_mov_b32_e32 v62, v10
	v_add_u32_e32 v10, 0x3000, v157
	ds_read2_b64 v[126:129], v10 offset0:96 offset1:100
	ds_read2_b64 v[200:203], v10 offset0:104 offset1:108
	ds_read2_b64 v[122:125], v10 offset0:112 offset1:116
	ds_read2_b64 v[204:207], v10 offset0:120 offset1:124
	v_add_u32_e32 v10, 0x8800, v156
	v_mov_b32_e32 v63, v11
	s_waitcnt lgkmcnt(9)
	v_mov_b32_e32 v64, v54
	v_mov_b32_e32 v65, v55
	v_mov_b32_e32 v54, v12
	v_mov_b32_e32 v55, v13
	ds_read2_b64 v[10:13], v10 offset1:4
	ds_read_b128 v[38:41], v196
	ds_read_b128 v[42:45], v198
	ds_read2_b64 v[208:211], v183 offset0:32 offset1:36
	v_add_u32_e32 v183, 0x9800, v156
	ds_read2_b64 v[212:215], v183 offset0:64 offset1:68
	ds_read_b128 v[216:219], v197
	ds_read_b128 v[220:223], v199
	s_waitcnt lgkmcnt(5)
	v_pk_mul_f32 v[40:41], v[100:101], v[40:41]
	v_pk_mul_f32 v[38:39], v[98:99], v[38:39]
	v_mfma_f32_16x16x32_bf16 v[54:57], v[58:61], v[54:57], 0
	v_add_u32_e32 v183, 0xa000, v156
	ds_read2_b64 v[224:227], v183 offset0:96 offset1:100
	v_add_u32_e32 v183, s34, v171
	v_mfma_f32_16x16x32_bf16 v[10:13], v[10:13], v[58:61], v[38:41]
	v_add_u32_e32 v98, s34, v173
	v_add_u32_e32 v99, 0xb800, v156
	v_add_u32_e32 v100, 0xc000, v156
	s_waitcnt lgkmcnt(5)
	v_pk_mul_f32 v[40:41], v[108:109], v[44:45]
	v_pk_mul_f32 v[38:39], v[106:107], v[42:43]
	s_waitcnt lgkmcnt(2)
	v_pk_mul_f32 v[44:45], v[112:113], v[218:219]
	v_pk_mul_f32 v[42:43], v[110:111], v[216:217]
	v_cvt_pk_bf16_f32 v110, v110, v111
	v_cvt_pk_bf16_f32 v111, v112, v113
	v_cvt_pk_bf16_f32 v112, v102, v103
	v_cvt_pk_bf16_f32 v113, v104, v105
	v_mfma_f32_16x16x32_bf16 v[62:65], v[58:61], v[62:65], 0
	v_add_u32_e32 v216, 0xb000, v156
	ds_read2_b64 v[228:231], v186 offset0:128 offset1:132
	v_add_u32_e32 v186, s34, v172
	v_mfma_f32_16x16x32_bf16 v[118:121], v[110:113], v[118:121], 0
	v_lshl_add_u64 v[138:139], v[138:139], 0, s[22:23]
	v_lshl_add_u64 v[140:141], v[140:141], 0, s[24:25]
	s_cmp_eq_u32 s31, 0
	v_mfma_f32_16x16x32_bf16 v[106:109], v[110:113], v[200:203], 0
	v_cvt_pk_bf16_f32 v110, v90, v91
	v_cvt_pk_bf16_f32 v111, v92, v93
	v_cvt_pk_bf16_f32 v112, v94, v95
	v_cvt_pk_bf16_f32 v113, v96, v97
	v_mfma_f32_16x16x32_bf16 v[54:57], v[232:235], v[126:129], v[54:57]
	v_cvt_pk_bf16_f32 v126, v82, v83
	v_cvt_pk_bf16_f32 v127, v84, v85
	v_cvt_pk_bf16_f32 v128, v86, v87
	v_cvt_pk_bf16_f32 v129, v88, v89
	v_mfma_f32_16x16x32_bf16 v[50:53], v[232:235], v[50:53], v[62:65]
	v_lshl_add_u64 v[144:145], v[144:145], 0, s[26:27]
	v_mfma_f32_16x16x32_bf16 v[114:117], v[110:113], v[114:117], v[118:121]
	v_mfma_f32_16x16x32_bf16 v[46:49], v[126:129], v[46:49], v[50:53]
	v_mfma_f32_16x16x32_bf16 v[106:109], v[110:113], v[204:207], v[106:109]
	s_waitcnt lgkmcnt(2)
	s_nop 2
	v_pk_mul_f32 v[52:53], v[104:105], v[222:223]
	s_nop 1
	v_pk_add_f32 v[48:49], v[116:117], v[48:49]
	v_pk_add_f32 v[46:47], v[114:115], v[46:47]
	v_mfma_f32_16x16x32_bf16 v[54:57], v[126:129], v[122:125], v[54:57]
	v_mul_f32_e64 v50, v102, v220
	v_mul_f32_e64 v51, v103, v221
	v_mfma_f32_16x16x32_bf16 v[38:41], v[208:211], v[58:61], v[38:41]
	v_mfma_f32_16x16x32_bf16 v[42:45], v[212:215], v[58:61], v[42:45]
	ds_read_b128 v[208:211], v183
	ds_read_b128 v[212:215], v186
	ds_read2_b64 v[216:219], v216 offset0:160 offset1:164
	ds_read2_b64 v[62:65], v99 offset0:192 offset1:196
	v_add_u32_e32 v99, s34, v174
	ds_read_b128 v[110:113], v98
	ds_read_b128 v[118:121], v99
	ds_read2_b64 v[200:203], v100 offset0:224 offset1:228
	ds_write_b128 v155, v[46:49]
	v_pk_add_f32 v[48:49], v[108:109], v[56:57]
	v_pk_add_f32 v[46:47], v[106:107], v[54:55]
	ds_write_b128 v155, v[46:49] offset:8448
	s_waitcnt lgkmcnt(0)
	s_barrier
	ds_read_b128 v[104:107], v154
	ds_read_b128 v[114:117], v154 offset:16
	ds_read_b128 v[122:125], v154 offset:32
	ds_read_b128 v[126:129], v154 offset:48
	s_waitcnt lgkmcnt(14)
	v_mfma_f32_16x16x32_bf16 v[46:49], v[224:227], v[58:61], v[50:53]
	s_waitcnt lgkmcnt(3)
	s_nop 1
	v_pk_mul_f32 v[50:51], v[106:107], v[106:107]
	v_pk_mul_f32 v[52:53], v[104:105], v[104:105]
	s_nop 0
	v_pk_mov_b32 v[54:55], v[52:53], v[50:51] op_sel:[1,0]
	v_mov_b32_e32 v53, v51
	v_pk_add_f32 v[50:51], v[54:55], v[52:53]
	s_waitcnt lgkmcnt(2)
	v_pk_mul_f32 v[52:53], v[116:117], v[116:117]
	v_pk_mul_f32 v[54:55], v[114:115], v[114:115]
	v_pk_add_f32 v[50:51], v[50:51], v[50:51] op_sel:[0,1] op_sel_hi:[1,0]
	v_pk_mov_b32 v[56:57], v[54:55], v[52:53] op_sel:[1,0]
	v_mov_b32_e32 v55, v53
	v_pk_add_f32 v[52:53], v[56:57], v[54:55]
	s_waitcnt lgkmcnt(0)
	v_mul_f32_e32 v54, v126, v126
	v_mul_f32_e32 v55, v127, v127
	v_pk_add_f32 v[52:53], v[52:53], v[52:53] op_sel:[0,1] op_sel_hi:[1,0]
	v_mov_b32_e32 v51, v54
	v_mov_b32_e32 v53, v55
	v_pk_add_f32 v[50:51], v[50:51], v[52:53]
	v_mul_f32_e32 v52, v123, v123
	v_mul_f32_e32 v54, v125, v125
	v_mul_f32_e32 v56, v128, v128
	v_mul_f32_e32 v57, v129, v129
	v_pk_fma_f32 v[52:53], v[122:123], v[122:123], v[52:53] op_sel_hi:[1,1,0]
	v_pk_fma_f32 v[54:55], v[124:125], v[124:125], v[54:55] op_sel_hi:[1,1,0]
	v_mov_b32_e32 v53, v56
	v_mov_b32_e32 v55, v57
	v_pk_add_f32 v[52:53], v[52:53], v[54:55]
	v_pk_mul_f32 v[56:57], v[88:89], v[214:215]
	v_pk_add_f32 v[50:51], v[50:51], v[52:53]
	v_pk_mul_f32 v[52:53], v[84:85], v[210:211]
	v_add_f32_e32 v54, v50, v51
	v_and_b32_e32 v51, 64, v177
	v_xor_b32_e32 v50, 1, v177
	v_add_u32_e32 v102, 64, v51
	v_cmp_lt_i32_e32 vcc, v50, v102
	v_pk_mul_f32 v[84:85], v[92:93], v[112:113]
	v_add_u32_e32 v92, 0, v165
	v_cndmask_b32_e32 v50, v177, v50, vcc
	v_lshlrev_b32_e32 v100, 2, v50
	ds_bpermute_b32 v55, v100, v54
	v_pk_mul_f32 v[50:51], v[82:83], v[208:209]
	s_waitcnt lgkmcnt(0)
	v_add_f32_e32 v82, v54, v55
	v_xor_b32_e32 v54, 2, v177
	v_cmp_lt_i32_e32 vcc, v54, v102
	v_mfma_f32_16x16x32_bf16 v[50:53], v[228:231], v[58:61], v[50:53]
	s_nop 0
	v_cndmask_b32_e32 v54, v177, v54, vcc
	v_lshlrev_b32_e32 v101, 2, v54
	ds_bpermute_b32 v83, v101, v82
	v_pk_mul_f32 v[54:55], v[86:87], v[212:213]
	s_waitcnt lgkmcnt(0)
	v_add_f32_e32 v86, v82, v83
	v_xor_b32_e32 v82, 4, v177
	v_cmp_lt_i32_e32 vcc, v82, v102
	v_mfma_f32_16x16x32_bf16 v[54:57], v[216:219], v[58:61], v[54:57]
	s_nop 0
	v_cndmask_b32_e32 v82, v177, v82, vcc
	v_lshlrev_b32_e32 v102, 2, v82
	ds_bpermute_b32 v87, v102, v86
	v_pk_mul_f32 v[82:83], v[90:91], v[110:111]
	s_nop 1
	v_mfma_f32_16x16x32_bf16 v[62:65], v[62:65], v[58:61], v[82:85]
	s_waitcnt lgkmcnt(0)
	s_nop 1
	v_add_f32_e32 v82, v86, v87
	v_fmamk_f32 v82, v82, 0x3c000000, v178
	v_mul_f32_e32 v83, 0x4b800000, v82
	v_cmp_gt_f32_e32 vcc, s35, v82
	v_pk_mul_f32 v[84:85], v[96:97], v[120:121]
	s_nop 0
	v_cndmask_b32_e32 v82, v82, v83, vcc
	v_rsq_f32_e32 v86, v82
	v_pk_mul_f32 v[82:83], v[94:95], v[118:119]
	s_nop 1
	v_mfma_f32_16x16x32_bf16 v[58:61], v[200:203], v[58:61], v[82:85]
	s_nop 2
	v_mul_f32_e32 v82, 0x45800000, v86
	v_cndmask_b32_e32 v90, v86, v82, vcc
	v_pk_mul_f32 v[108:109], v[104:105], v[90:91] op_sel_hi:[1,0]
	v_add_u32_e32 v91, 0x1a000, v92
	ds_read_b128 v[82:85], v91
	v_pk_mul_f32 v[110:111], v[106:107], v[90:91] op_sel_hi:[1,0]
	ds_read_b128 v[86:89], v91 offset:16
	ds_read_b128 v[94:97], v91 offset:32
	ds_read_b128 v[104:107], v91 offset:48
	s_waitcnt lgkmcnt(3)
	v_pk_mul_f32 v[82:83], v[82:83], v[108:109]
	v_lshlrev_b32_e32 v108, 16, v26
	v_and_b32_e32 v109, 0xffff0000, v26
	v_pk_mul_f32 v[82:83], v[82:83], v[108:109]
	v_pk_mul_f32 v[84:85], v[84:85], v[110:111]
	v_cvt_pk_bf16_f32 v26, v82, v83
	v_lshlrev_b32_e32 v82, 16, v27
	v_and_b32_e32 v83, 0xffff0000, v27
	v_pk_mul_f32 v[82:83], v[84:85], v[82:83]
	v_pk_mul_f32 v[84:85], v[116:117], v[90:91] op_sel_hi:[1,0]
	v_cvt_pk_bf16_f32 v27, v82, v83
	v_pk_mul_f32 v[82:83], v[114:115], v[90:91] op_sel_hi:[1,0]
	s_waitcnt lgkmcnt(2)
	v_pk_mul_f32 v[84:85], v[88:89], v[84:85]
	v_pk_mul_f32 v[82:83], v[86:87], v[82:83]
	v_lshlrev_b32_e32 v86, 16, v28
	v_and_b32_e32 v87, 0xffff0000, v28
	v_pk_mul_f32 v[82:83], v[82:83], v[86:87]
	v_lshlrev_b32_e32 v86, 16, v14
	v_cvt_pk_bf16_f32 v28, v82, v83
	v_lshlrev_b32_e32 v82, 16, v29
	v_and_b32_e32 v83, 0xffff0000, v29
	v_pk_mul_f32 v[82:83], v[84:85], v[82:83]
	v_and_b32_e32 v87, 0xffff0000, v14
	v_cvt_pk_bf16_f32 v29, v82, v83
	v_pk_mul_f32 v[82:83], v[122:123], v[90:91] op_sel_hi:[1,0]
	v_pk_mul_f32 v[84:85], v[124:125], v[90:91] op_sel_hi:[1,0]
	s_waitcnt lgkmcnt(1)
	v_pk_mul_f32 v[82:83], v[94:95], v[82:83]
	v_pk_mul_f32 v[84:85], v[96:97], v[84:85]
	v_pk_mul_f32 v[82:83], v[82:83], v[86:87]
	v_lshlrev_b32_e32 v86, 16, v16
	v_cvt_pk_bf16_f32 v14, v82, v83
	v_lshlrev_b32_e32 v82, 16, v15
	v_and_b32_e32 v83, 0xffff0000, v15
	v_pk_mul_f32 v[82:83], v[84:85], v[82:83]
	v_and_b32_e32 v87, 0xffff0000, v16
	v_cvt_pk_bf16_f32 v15, v82, v83
	v_pk_mul_f32 v[82:83], v[126:127], v[90:91] op_sel_hi:[1,0]
	v_pk_mul_f32 v[84:85], v[128:129], v[90:91] op_sel_hi:[1,0]
	s_waitcnt lgkmcnt(0)
	v_pk_mul_f32 v[82:83], v[104:105], v[82:83]
	v_pk_mul_f32 v[84:85], v[106:107], v[84:85]
	v_pk_mul_f32 v[82:83], v[82:83], v[86:87]
	s_nop 0
	v_cvt_pk_bf16_f32 v16, v82, v83
	v_lshlrev_b32_e32 v82, 16, v17
	v_and_b32_e32 v83, 0xffff0000, v17
	v_pk_mul_f32 v[82:83], v[84:85], v[82:83]
	s_nop 0
	v_cvt_pk_bf16_f32 v17, v82, v83
	v_add_co_u32_e32 v82, vcc, s36, v146
	s_nop 1
	v_addc_co_u32_e32 v83, vcc, 0, v147, vcc
	global_store_dwordx4 v[82:83], v[26:29], off
	global_store_dwordx4 v[82:83], v[14:17], off offset:16
	s_cbranch_scc1 .LBB0_356
	s_waitcnt vmcnt(11)
	v_mov_b64_e32 v[28:29], v[8:9]
	s_waitcnt vmcnt(10)
	v_mov_b64_e32 v[16:17], v[4:5]
	v_mov_b64_e32 v[26:27], v[6:7]
	v_mov_b64_e32 v[14:15], v[2:3]
	s_branch .LBB0_350

.LBB0_534:
	v_mov_b32_e32 v131, 0
	s_lshl_b64 s[10:11], s[56:57], 12
	v_lshl_add_u64 v[68:69], s[4:5], 0, v[130:131]
	s_movk_i32 s3, 0x1000
	s_add_u32 s10, s40, s10
	v_add_co_u32_e32 v68, vcc, s3, v68
	s_addc_u32 s11, s41, s11
	v_lshlrev_b32_e32 v66, 3, v142
	v_addc_co_u32_e32 v69, vcc, 0, v69, vcc
	global_load_dwordx4 v[114:117], v130, s[4:5] offset:3072
	global_load_dwordx4 v[118:121], v130, s[4:5] offset:2048
	global_load_dwordx4 v[98:101], v[68:69], off offset:3072
	global_load_dwordx4 v[102:105], v[68:69], off offset:2048
	global_load_dwordx4 v[106:109], v[68:69], off offset:1024
	global_load_dwordx4 v[110:113], v[68:69], off
	global_load_dwordx4 v[122:125], v130, s[4:5] offset:1024
	global_load_dwordx4 v[126:129], v130, s[4:5]
	global_load_dwordx2 v[168:169], v66, s[10:11] nt
	global_load_dwordx2 v[166:167], v66, s[10:11] offset:512 nt
	global_load_dwordx2 v[164:165], v66, s[10:11] offset:1024 nt
	global_load_dwordx2 v[162:163], v66, s[10:11] offset:1536 nt
	global_load_dwordx2 v[160:161], v66, s[10:11] offset:2048 nt
	global_load_dwordx2 v[158:159], v66, s[10:11] offset:2560 nt
	global_load_dwordx2 v[156:157], v66, s[10:11] offset:3072 nt
	global_load_dwordx2 v[154:155], v66, s[10:11] offset:3584 nt
	v_mbcnt_lo_u32_b32 v68, -1, 0
	v_mbcnt_hi_u32_b32 v68, -1, v68
	v_and_b32_e32 v69, 64, v68
	v_xor_b32_e32 v70, 1, v68
	v_add_u32_e32 v69, 64, v69
	v_xor_b32_e32 v71, 2, v68
	v_cmp_lt_i32_e32 vcc, v70, v69
	v_xor_b32_e32 v72, 4, v68
	v_xor_b32_e32 v73, 8, v68
	v_cndmask_b32_e32 v70, v68, v70, vcc
	v_cmp_lt_i32_e32 vcc, v71, v69
	s_lshl_b64 s[8:9], s[8:9], 12
	v_xor_b32_e32 v74, 16, v68
	v_cndmask_b32_e32 v71, v68, v71, vcc
	v_cmp_lt_i32_e32 vcc, v72, v69
	s_add_u32 s10, s70, s8
	v_mov_b32_e32 v67, v131
	v_cndmask_b32_e32 v72, v68, v72, vcc
	v_cmp_lt_i32_e32 vcc, v73, v69
	v_xor_b32_e32 v75, 32, v68
	s_addc_u32 s11, s71, s9
	v_cndmask_b32_e32 v73, v68, v73, vcc
	v_cmp_lt_i32_e32 vcc, v74, v69
	s_add_i32 s8, s56, s64
	s_mov_b64 s[12:13], 0x1d000000
	v_lshl_add_u64 v[132:133], s[40:41], 0, v[66:67]
	v_cndmask_b32_e32 v74, v68, v74, vcc
	v_cmp_lt_i32_e32 vcc, v75, v69
	s_ashr_i32 s65, s64, 31
	v_lshl_add_u64 v[66:67], s[10:11], 0, v[66:67]
	s_ashr_i32 s9, s8, 31
	v_cndmask_b32_e32 v68, v68, v75, vcc
	s_lshl_b64 s[10:11], s[64:65], 12
	v_lshl_add_u64 v[134:135], v[66:67], 0, s[12:13]
	s_lshl_b64 s[12:13], s[8:9], 13
	v_readlane_b32 s76, v242, 31
	v_lshlrev_b32_e32 v170, 2, v70
	v_lshlrev_b32_e32 v171, 2, v71
	v_lshlrev_b32_e32 v172, 2, v72
	v_lshlrev_b32_e32 v173, 2, v73
	v_lshlrev_b32_e32 v174, 2, v74
	v_lshlrev_b32_e32 v175, 2, v68
	v_readlane_b32 s77, v242, 32
	s_add_u32 s12, s76, s12
	s_mov_b32 s5, 0
	v_mov_b32_e32 v1, 0x358637bd
	s_mov_b32 s3, 0x800000
	s_mov_b32 s26, 0xef000000
	s_mov_b32 s27, 0xef001000
	s_mov_b32 s28, s56
	s_addc_u32 s13, s77, s13
	s_lshl_b64 s[20:21], s[64:65], 13
	s_mov_b64 s[16:17], s[30:31]
	v_readlane_b32 s78, v242, 33
	v_readlane_b32 s79, v242, 34
	v_readlane_b32 s80, v242, 35
	v_readlane_b32 s81, v242, 36
	v_readlane_b32 s82, v242, 37
	v_readlane_b32 s83, v242, 38
	v_readlane_b32 s84, v242, 39
	v_readlane_b32 s85, v242, 40
	v_readlane_b32 s86, v242, 41
	v_readlane_b32 s87, v242, 42
	v_readlane_b32 s88, v242, 43
	s_waitcnt vmcnt(15)
	v_mov_b64_e32 v[66:67], v[114:115]
	s_waitcnt vmcnt(14)
	v_mov_b64_e32 v[70:71], v[118:119]
	s_waitcnt vmcnt(13)
	v_mov_b64_e32 v[82:83], v[98:99]
	s_waitcnt vmcnt(12)
	v_mov_b64_e32 v[86:87], v[102:103]
	s_waitcnt vmcnt(11)
	v_mov_b64_e32 v[90:91], v[106:107]
	s_waitcnt vmcnt(10)
	v_mov_b64_e32 v[94:95], v[110:111]
	s_waitcnt vmcnt(9)
	v_mov_b64_e32 v[74:75], v[122:123]
	s_waitcnt vmcnt(8)
	v_mov_b64_e32 v[78:79], v[126:127]
	v_mov_b64_e32 v[68:69], v[116:117]
	v_mov_b64_e32 v[72:73], v[120:121]
	v_mov_b64_e32 v[84:85], v[100:101]
	v_mov_b64_e32 v[88:89], v[104:105]
	v_mov_b64_e32 v[92:93], v[108:109]
	v_mov_b64_e32 v[96:97], v[112:113]
	v_mov_b64_e32 v[76:77], v[124:125]
	v_mov_b64_e32 v[80:81], v[128:129]
	s_waitcnt vmcnt(7)
	v_mov_b64_e32 v[136:137], v[168:169]
	s_waitcnt vmcnt(6)
	v_mov_b64_e32 v[138:139], v[166:167]
	s_waitcnt vmcnt(5)
	v_mov_b64_e32 v[140:141], v[164:165]
	s_waitcnt vmcnt(4)
	v_mov_b64_e32 v[144:145], v[162:163]
	s_waitcnt vmcnt(3)
	v_mov_b64_e32 v[146:147], v[160:161]
	s_waitcnt vmcnt(2)
	v_mov_b64_e32 v[148:149], v[158:159]
	s_waitcnt vmcnt(1)
	v_mov_b64_e32 v[150:151], v[156:157]
	s_waitcnt vmcnt(0)
	v_mov_b64_e32 v[152:153], v[154:155]
	v_readlane_b32 s89, v242, 44
	v_readlane_b32 s90, v242, 45
	v_readlane_b32 s91, v242, 46
	s_branch .LBB0_537
.LBB0_535:
	v_lshl_add_u64 v[82:83], s[24:25], 0, v[130:131]
	v_add_co_u32_e32 v82, vcc, 0x1000, v82
	s_lshl_b64 s[22:23], s[22:23], 12
	s_nop 0
	v_addc_co_u32_e32 v83, vcc, 0, v83, vcc
	v_lshl_add_u64 v[152:153], v[132:133], 0, s[22:23]
	global_load_dwordx4 v[78:81], v130, s[24:25]
	global_load_dwordx4 v[74:77], v130, s[24:25] offset:1024
	global_load_dwordx4 v[70:73], v130, s[24:25] offset:2048
	global_load_dwordx4 v[66:69], v130, s[24:25] offset:3072
	global_load_dwordx4 v[94:97], v[82:83], off
	global_load_dwordx4 v[90:93], v[82:83], off offset:1024
	global_load_dwordx4 v[86:89], v[82:83], off offset:2048
	s_nop 0
	global_load_dwordx4 v[82:85], v[82:83], off offset:3072
	s_nop 0
	global_load_dwordx2 v[136:137], v[152:153], off nt
	global_load_dwordx2 v[138:139], v[152:153], off offset:512 nt
	global_load_dwordx2 v[140:141], v[152:153], off offset:1024 nt
	global_load_dwordx2 v[144:145], v[152:153], off offset:1536 nt
	global_load_dwordx2 v[146:147], v[152:153], off offset:2048 nt
	global_load_dwordx2 v[148:149], v[152:153], off offset:2560 nt
	global_load_dwordx2 v[150:151], v[152:153], off offset:3072 nt
	s_nop 0
	global_load_dwordx2 v[152:153], v[152:153], off offset:3584 nt

.LBB0_788:
.LBB0_789:
	s_cmp_lt_i32 s72, 9
	s_cselect_b64 s[4:5], -1, 0
	s_and_b64 s[0:1], s[4:5], s[0:1]
	s_andn2_b64 vcc, exec, s[0:1]
	s_cbranch_vccnz .LBB0_796
	s_cmpk_gt_i32 s56, 0x21ff
	s_cbranch_scc1 .LBB0_796
	v_readlane_b32 s76, v242, 12
	v_readlane_b32 s77, v242, 13
	v_readlane_b32 s78, v242, 14
	v_readlane_b32 s79, v242, 15
	v_readlane_b32 s80, v242, 16
	v_readlane_b32 s81, v242, 17
	v_readlane_b32 s82, v242, 18
	v_readlane_b32 s83, v242, 19
	v_readlane_b32 s84, v242, 20
	v_readlane_b32 s85, v242, 21
	v_readlane_b32 s86, v242, 22
	v_readlane_b32 s87, v242, 23
	v_readlane_b32 s88, v242, 24
	v_readlane_b32 s89, v242, 25
	v_readlane_b32 s90, v242, 26
	v_readlane_b32 s91, v242, 27
	s_mov_b64 s[8:9], s[76:77]
	s_mov_b64 s[18:19], s[86:87]
	v_readlane_b32 s76, v242, 31
	s_waitcnt vmcnt(0)
	v_lshlrev_b32_e32 v98, 4, v142
	v_mov_b32_e32 v99, 0
	v_readlane_b32 s86, v242, 41
	v_readlane_b32 s87, v242, 42
	v_lshl_add_u64 v[50:51], s[8:9], 0, v[98:99]
	s_mov_b64 s[4:5], 0x2000
	v_lshl_add_u64 v[52:53], s[86:87], 0, v[98:99]
	v_add_co_u32_e32 v34, vcc, 0x2000, v52
	v_lshl_add_u64 v[38:39], v[52:53], 0, s[4:5]
	s_nop 0
	v_addc_co_u32_e32 v35, vcc, 0, v53, vcc
	v_add_co_u32_e32 v78, vcc, 0x1000, v50
	global_load_dwordx4 v[2:5], v98, s[8:9]
	global_load_dwordx4 v[6:9], v98, s[18:19]
	global_load_dwordx4 v[10:13], v98, s[8:9] offset:1024
	global_load_dwordx4 v[14:17], v98, s[18:19] offset:1024
	global_load_dwordx4 v[18:21], v[38:39], off offset:1024
	global_load_dwordx4 v[22:25], v[38:39], off offset:2048
	global_load_dwordx4 v[26:29], v98, s[8:9] offset:2048
	global_load_dwordx4 v[30:33], v98, s[18:19] offset:2048
	s_nop 0
	global_load_dwordx4 v[34:37], v[34:35], off
	s_nop 0
	global_load_dwordx4 v[38:41], v[38:39], off offset:3072
	s_nop 0
	global_load_dwordx4 v[42:45], v98, s[8:9] offset:3072
	global_load_dwordx4 v[46:49], v98, s[18:19] offset:3072
	v_addc_co_u32_e32 v79, vcc, 0, v51, vcc
	v_add_co_u32_e32 v86, vcc, 0x3000, v52
	v_lshl_add_u64 v[54:55], s[18:19], 0, v[98:99]
	s_nop 0
	v_addc_co_u32_e32 v87, vcc, 0, v53, vcc
	v_add_co_u32_e32 v94, vcc, 0x1000, v54
	s_ashr_i32 s57, s56, 31
	s_nop 0
	v_addc_co_u32_e32 v95, vcc, 0, v55, vcc
	global_load_dwordx4 v[50:53], v[78:79], off
	global_load_dwordx4 v[54:57], v[78:79], off offset:1024
	global_load_dwordx4 v[58:61], v[86:87], off
	global_load_dwordx4 v[62:65], v[86:87], off offset:1024
	global_load_dwordx4 v[66:69], v[94:95], off
	global_load_dwordx4 v[70:73], v[94:95], off offset:1024
	global_load_dwordx4 v[74:77], v[78:79], off offset:2048
	s_nop 0
	global_load_dwordx4 v[78:81], v[78:79], off offset:3072
	s_lshl_b64 s[4:5], s[56:57], 12
	v_readlane_b32 s6, v242, 51
	v_readlane_b32 s7, v242, 52
	s_add_u32 s6, s6, s4
	s_addc_u32 s7, s7, s5
	s_add_u32 s8, s40, s4
	v_lshlrev_b32_e32 v98, 3, v142
	s_addc_u32 s9, s41, s5
	global_load_dwordx2 v[154:155], v98, s[8:9] offset:2048 nt
	global_load_dwordx2 v[152:153], v98, s[8:9] offset:2560 nt
	global_load_dwordx2 v[150:151], v98, s[8:9] offset:3072 nt
	global_load_dwordx2 v[148:149], v98, s[8:9] offset:3584 nt
	global_load_dwordx2 v[162:163], v98, s[8:9] nt
	global_load_dwordx2 v[160:161], v98, s[8:9] offset:512 nt
	global_load_dwordx2 v[158:159], v98, s[8:9] offset:1024 nt
	global_load_dwordx2 v[156:157], v98, s[8:9] offset:1536 nt
	global_load_dwordx4 v[82:85], v[86:87], off offset:2048
	s_nop 0
	global_load_dwordx4 v[86:89], v[86:87], off offset:3072
	s_nop 0
	global_load_dwordx2 v[164:165], v98, s[6:7] nt
	global_load_dwordx2 v[146:147], v98, s[6:7] offset:512 nt
	global_load_dwordx2 v[144:145], v98, s[6:7] offset:1024 nt
	global_load_dwordx2 v[140:141], v98, s[6:7] offset:1536 nt
	global_load_dwordx2 v[138:139], v98, s[6:7] offset:2048 nt
	global_load_dwordx2 v[136:137], v98, s[6:7] offset:2560 nt
	global_load_dwordx2 v[134:135], v98, s[6:7] offset:3072 nt
	global_load_dwordx2 v[132:133], v98, s[6:7] offset:3584 nt
	global_load_dwordx4 v[90:93], v[94:95], off offset:2048
	s_nop 0
	global_load_dwordx4 v[94:97], v[94:95], off offset:3072
	v_mbcnt_lo_u32_b32 v1, -1, 0
	v_mbcnt_hi_u32_b32 v100, -1, v1
	v_and_b32_e32 v1, 64, v100
	v_add_u32_e32 v101, 64, v1
	v_xor_b32_e32 v1, 1, v100
	v_cmp_lt_i32_e32 vcc, v1, v101
	v_xor_b32_e32 v102, 2, v100
	s_add_u32 s4, s70, s4
	v_cndmask_b32_e32 v1, v100, v1, vcc
	v_cmp_lt_i32_e32 vcc, v102, v101
	s_addc_u32 s5, s71, s5
	s_add_i32 s8, s56, s64
	v_cndmask_b32_e32 v102, v100, v102, vcc
	v_lshlrev_b32_e32 v166, 2, v102
	v_xor_b32_e32 v102, 4, v100
	v_cmp_lt_i32_e32 vcc, v102, v101
	s_ashr_i32 s65, s64, 31
	s_ashr_i32 s9, s8, 31
	v_cndmask_b32_e32 v102, v100, v102, vcc
	v_lshlrev_b32_e32 v167, 2, v102
	v_xor_b32_e32 v102, 8, v100
	v_cmp_lt_i32_e32 vcc, v102, v101
	s_lshl_b64 s[6:7], s[64:65], 12
	s_lshl_b64 s[8:9], s[8:9], 12
	v_cndmask_b32_e32 v102, v100, v102, vcc
	v_lshlrev_b32_e32 v168, 2, v102
	v_xor_b32_e32 v102, 16, v100
	v_cmp_lt_i32_e32 vcc, v102, v101
	s_add_u32 s8, s70, s8
	v_lshlrev_b32_e32 v1, 2, v1
	v_cndmask_b32_e32 v102, v100, v102, vcc
	v_lshlrev_b32_e32 v169, 2, v102
	v_xor_b32_e32 v102, 32, v100
	v_cmp_lt_i32_e32 vcc, v102, v101
	s_addc_u32 s9, s71, s9
	s_mov_b32 s3, 0x1d000000
	v_cndmask_b32_e32 v100, v100, v102, vcc
	v_lshlrev_b32_e32 v170, 2, v100
	v_mov_b32_e32 v171, 0x358637bd
	s_mov_b32 s12, 0x800000
	s_brev_b32 s13, 48
	s_mov_b32 s18, 0x14800000
	s_mov_b32 s19, s56
	v_readlane_b32 s77, v242, 32
	v_readlane_b32 s78, v242, 33
	v_readlane_b32 s79, v242, 34
	v_readlane_b32 s80, v242, 35
	v_readlane_b32 s81, v242, 36
	v_readlane_b32 s82, v242, 37
	v_readlane_b32 s83, v242, 38
	v_readlane_b32 s84, v242, 39
	v_readlane_b32 s85, v242, 40
	v_readlane_b32 s88, v242, 43
	v_readlane_b32 s89, v242, 44
	v_readlane_b32 s90, v242, 45
	v_readlane_b32 s91, v242, 46
	s_waitcnt vmcnt(19)
	v_mov_b64_e32 v[118:119], v[154:155]
	s_waitcnt vmcnt(18)
	v_mov_b64_e32 v[116:117], v[152:153]
	s_waitcnt vmcnt(17)
	v_mov_b64_e32 v[114:115], v[150:151]
	s_waitcnt vmcnt(16)
	v_mov_b64_e32 v[112:113], v[148:149]
	s_waitcnt vmcnt(15)
	v_mov_b64_e32 v[126:127], v[162:163]
	s_waitcnt vmcnt(14)
	v_mov_b64_e32 v[124:125], v[160:161]
	s_waitcnt vmcnt(13)
	v_mov_b64_e32 v[122:123], v[158:159]
	s_waitcnt vmcnt(12)
	v_mov_b64_e32 v[120:121], v[156:157]
	s_waitcnt vmcnt(9)
	v_mov_b64_e32 v[100:101], v[164:165]
	s_waitcnt vmcnt(8)
	v_mov_b64_e32 v[102:103], v[146:147]
	s_waitcnt vmcnt(7)
	v_mov_b64_e32 v[104:105], v[144:145]
	s_waitcnt vmcnt(6)
	v_mov_b64_e32 v[106:107], v[140:141]
	s_waitcnt vmcnt(5)
	v_mov_b64_e32 v[108:109], v[138:139]
	s_waitcnt vmcnt(4)
	v_mov_b64_e32 v[110:111], v[136:137]
	s_waitcnt vmcnt(3)
	v_mov_b64_e32 v[128:129], v[134:135]
	s_waitcnt vmcnt(2)
	v_mov_b64_e32 v[130:131], v[132:133]
	s_branch .LBB0_793

.LBB0_793:
	s_add_i32 s19, s19, s64
	s_cmpk_gt_i32 s19, 0x21ff
	s_cselect_b64 s[10:11], -1, 0
	s_and_b64 vcc, exec, s[10:11]
	s_cbranch_vccnz .LBB0_792
	v_lshl_add_u64 v[112:113], s[8:9], 0, v[98:99]
	v_add_co_u32_e32 v114, vcc, 0x1d000000, v112
	s_nop 1
	v_addc_co_u32_e32 v115, vcc, 0, v113, vcc
	v_add_co_u32_e32 v112, vcc, 0xe200000, v112
	global_load_dwordx2 v[100:101], v[114:115], off nt
	global_load_dwordx2 v[102:103], v[114:115], off offset:512 nt
	global_load_dwordx2 v[104:105], v[114:115], off offset:1024 nt
	global_load_dwordx2 v[106:107], v[114:115], off offset:1536 nt
	global_load_dwordx2 v[108:109], v[114:115], off offset:2048 nt
	global_load_dwordx2 v[110:111], v[114:115], off offset:2560 nt
	global_load_dwordx2 v[128:129], v[114:115], off offset:3072 nt
	global_load_dwordx2 v[130:131], v[114:115], off offset:3584 nt
	v_addc_co_u32_e32 v113, vcc, 0, v113, vcc
	global_load_dwordx2 v[126:127], v[112:113], off nt
	global_load_dwordx2 v[124:125], v[112:113], off offset:512 nt
	global_load_dwordx2 v[122:123], v[112:113], off offset:1024 nt
	global_load_dwordx2 v[120:121], v[112:113], off offset:1536 nt
	global_load_dwordx2 v[118:119], v[112:113], off offset:2048 nt
	global_load_dwordx2 v[116:117], v[112:113], off offset:2560 nt
	global_load_dwordx2 v[114:115], v[112:113], off offset:3072 nt
	s_nop 0
	global_load_dwordx2 v[112:113], v[112:113], off offset:3584 nt
	s_branch .LBB0_792

.LBB0_1034:
	v_readlane_b32 s0, v242, 55
	v_readlane_b32 s1, v242, 56
	s_add_i32 s3, s0, 0xfffffd60
	s_cmpk_gt_i32 s3, 0x394
	s_mov_b64 s[0:1], -1
	s_cbranch_scc0 .LBB0_1041
	v_readlane_b32 s0, v242, 55
	s_addk_i32 s0, 0xf9cb
	s_cmpk_gt_u32 s0, 0x15ff
	v_readlane_b32 s1, v242, 56
	s_cbranch_scc1 .LBB0_1040
	v_readlane_b32 s4, v242, 0
	v_readlane_b32 s10, v242, 6
	v_readlane_b32 s5, v242, 1
	v_readlane_b32 s11, v242, 7
	s_add_u32 s4, s10, 0x2c00000
	s_addc_u32 s5, s11, 0
	s_lshl_b32 s1, s0, 7
	v_readlane_b32 s6, v242, 2
	s_and_b32 s1, s1, 0x1f80
	v_readlane_b32 s7, v242, 3
	s_add_u32 s6, s4, s1
	v_lshrrev_b32_e32 v1, 3, v142
	s_addc_u32 s7, s5, 0
	v_and_b32_e32 v38, 7, v143
	s_and_b32 s0, s0, 0x1fc0
	v_lshlrev_b32_e32 v34, 4, v38
	v_mov_b32_e32 v35, 0
	v_or_b32_e32 v4, s0, v1
	v_lshl_add_u64 v[2:3], s[6:7], 0, v[34:35]
	v_lshlrev_b32_e32 v4, 13, v4
	v_mov_b32_e32 v5, v35
	v_lshl_add_u64 v[26:27], v[2:3], 0, v[4:5]
	s_mov_b32 s0, 0x10000
	v_add_co_u32_e32 v6, vcc, s0, v26
	s_mov_b32 s0, 0x20000
	s_nop 0
	v_addc_co_u32_e32 v7, vcc, 0, v27, vcc
	v_add_co_u32_e32 v10, vcc, s0, v26
	s_mov_b32 s0, 0x30000
	s_nop 0
	v_addc_co_u32_e32 v11, vcc, 0, v27, vcc
	v_add_co_u32_e32 v14, vcc, s0, v26
	s_mov_b32 s0, 0x40000
	s_nop 0
	v_addc_co_u32_e32 v15, vcc, 0, v27, vcc
	v_add_co_u32_e32 v18, vcc, s0, v26
	s_mov_b32 s0, 0x50000
	s_nop 0
	v_addc_co_u32_e32 v19, vcc, 0, v27, vcc
	v_add_co_u32_e32 v22, vcc, s0, v26
	s_mov_b32 s0, 0x60000
	s_nop 0
	v_addc_co_u32_e32 v23, vcc, 0, v27, vcc
	v_add_co_u32_e32 v28, vcc, s0, v26
	s_mov_b32 s0, 0x70000
	s_nop 0
	v_addc_co_u32_e32 v29, vcc, 0, v27, vcc
	v_add_co_u32_e32 v30, vcc, s0, v26
	global_load_dwordx4 v[2:5], v[26:27], off nt
	s_nop 0
	global_load_dwordx4 v[6:9], v[6:7], off nt
	v_addc_co_u32_e32 v31, vcc, 0, v27, vcc
	global_load_dwordx4 v[10:13], v[10:11], off nt
	s_nop 0
	global_load_dwordx4 v[14:17], v[14:15], off nt
	s_nop 0
	global_load_dwordx4 v[18:21], v[18:19], off nt
	s_nop 0
	global_load_dwordx4 v[22:25], v[22:23], off nt
	s_nop 0
	global_load_dwordx4 v[26:29], v[28:29], off nt
	s_nop 0
	global_load_dwordx4 v[30:33], v[30:31], off nt
	v_lshl_add_u64 v[36:37], s[4:5], 0, v[34:35]
	v_readlane_b32 s4, v242, 55
	v_readlane_b32 s0, v242, 29
	v_readlane_b32 s5, v242, 56
	v_mul_u32_u24_e32 v40, 0x420, v38
	v_add_u32_e32 v44, s0, v34
	v_lshl_add_u64 v[38:39], s[46:47], 0, v[34:35]
	v_lshlrev_b32_e32 v34, 2, v1
	v_readlane_b32 s5, v242, 28
	v_add3_u32 v40, s0, v40, v34
	v_mul_u32_u24_e32 v34, 0x84, v1
	s_add_i32 s0, s4, 0xfffff800
	s_lshl_b32 s4, s2, 8
	s_lshl_b32 s5, s5, 5
	s_mov_b32 s1, 0
	v_or_b32_e32 v41, 8, v1
	v_or_b32_e32 v42, 16, v1
	v_or_b32_e32 v43, 24, v1
	s_add_i32 s6, s4, s5
	v_add_u32_e32 v44, v44, v34
	v_readlane_b32 s8, v242, 4
	v_readlane_b32 s9, v242, 5
	s_branch .LBB0_1038

.LBB0_1038:
	v_add_u32_e32 v34, 0x420, v44
	s_waitcnt vmcnt(0)
	ds_write2_b32 v44, v2, v3 offset1:1
	ds_write2_b32 v44, v4, v5 offset0:2 offset1:3
	ds_write2_b32 v34, v6, v7 offset1:1
	v_add_u32_e32 v34, 0x428, v44
	ds_write2_b32 v34, v8, v9 offset1:1
	v_add_u32_e32 v34, 0x840, v44
	ds_write2_b32 v34, v10, v11 offset1:1
	v_add_u32_e32 v34, 0x848, v44
	ds_write2_b32 v34, v12, v13 offset1:1
	v_add_u32_e32 v34, 0xc60, v44
	ds_write2_b32 v34, v14, v15 offset1:1
	v_add_u32_e32 v34, 0xc68, v44
	ds_write2_b32 v34, v16, v17 offset1:1
	v_add_u32_e32 v34, 0x1080, v44
	ds_write2_b32 v34, v18, v19 offset1:1
	v_add_u32_e32 v34, 0x1088, v44
	ds_write2_b32 v34, v20, v21 offset1:1
	v_add_u32_e32 v34, 0x14a0, v44
	ds_write2_b32 v34, v22, v23 offset1:1
	v_add_u32_e32 v34, 0x14a8, v44
	s_add_i32 s7, s0, 0x1cb
	ds_write2_b32 v34, v24, v25 offset1:1
	v_add_u32_e32 v34, 0x18c0, v44
	ds_write2_b32 v34, v26, v27 offset1:1
	v_add_u32_e32 v34, 0x18c8, v44
	s_cmpk_gt_i32 s7, 0x1434
	ds_write2_b32 v34, v28, v29 offset1:1
	v_add_u32_e32 v34, 0x1ce0, v44
	s_cselect_b64 s[4:5], -1, 0
	ds_write2_b32 v34, v30, v31 offset1:1
	v_add_u32_e32 v34, 0x1ce8, v44
	s_and_b64 vcc, exec, s[4:5]
	ds_write2_b32 v34, v32, v33 offset1:1
	s_cbranch_vccnz .LBB0_1037
	s_addk_i32 s0, 0x396
	s_and_b32 s0, s0, 0x7fffffc0
	s_add_i32 s8, s6, 0xffff72c0
	s_and_b32 s8, s8, 0x7e0
	v_or_b32_e32 v34, s0, v1
	s_lshl_b32 s0, s8, 2
	v_lshlrev_b64 v[2:3], 13, v[34:35]
	v_or_b32_e32 v4, 8, v34
	v_mov_b32_e32 v5, v35
	v_or_b32_e32 v10, 16, v34
	v_mov_b32_e32 v11, v35
	v_or_b32_e32 v12, 24, v34
	v_mov_b32_e32 v13, v35
	v_or_b32_e32 v18, 32, v34
	v_mov_b32_e32 v19, v35
	v_or_b32_e32 v20, 40, v34
	v_mov_b32_e32 v21, v35
	v_or_b32_e32 v28, 48, v34
	v_mov_b32_e32 v29, v35
	v_or_b32_e32 v34, 56, v34
	v_lshl_add_u64 v[26:27], v[36:37], 0, s[0:1]
	v_lshlrev_b64 v[4:5], 13, v[4:5]
	v_lshlrev_b64 v[10:11], 13, v[10:11]
	v_lshlrev_b64 v[12:13], 13, v[12:13]
	v_lshlrev_b64 v[18:19], 13, v[18:19]
	v_lshlrev_b64 v[20:21], 13, v[20:21]
	v_lshlrev_b64 v[28:29], 13, v[28:29]
	v_lshlrev_b64 v[30:31], 13, v[34:35]
	v_lshl_add_u64 v[2:3], v[26:27], 0, v[2:3]
	v_lshl_add_u64 v[6:7], v[26:27], 0, v[4:5]
	v_lshl_add_u64 v[10:11], v[26:27], 0, v[10:11]
	v_lshl_add_u64 v[14:15], v[26:27], 0, v[12:13]
	v_lshl_add_u64 v[18:19], v[26:27], 0, v[18:19]
	v_lshl_add_u64 v[22:23], v[26:27], 0, v[20:21]
	v_lshl_add_u64 v[28:29], v[26:27], 0, v[28:29]
	v_lshl_add_u64 v[30:31], v[26:27], 0, v[30:31]
	global_load_dwordx4 v[2:5], v[2:3], off nt
	s_nop 0
	global_load_dwordx4 v[6:9], v[6:7], off nt
	s_nop 0
	global_load_dwordx4 v[10:13], v[10:11], off nt
	s_nop 0
	global_load_dwordx4 v[14:17], v[14:15], off nt
	s_nop 0
	global_load_dwordx4 v[18:21], v[18:19], off nt
	s_nop 0
	global_load_dwordx4 v[22:25], v[22:23], off nt
	s_nop 0
	global_load_dwordx4 v[26:29], v[28:29], off nt
	s_nop 0
	global_load_dwordx4 v[30:33], v[30:31], off nt
	s_branch .LBB0_1037

.LBB0_1041:
	s_andn2_b64 vcc, exec, s[0:1]
	s_cbranch_vccnz .LBB0_1046
	v_readlane_b32 s4, v242, 0
	v_readlane_b32 s5, v242, 1
	v_readlane_b32 s8, v242, 4
	v_readlane_b32 s9, v242, 5
	s_mov_b64 s[4:5], s[8:9]
	s_add_u32 s0, s4, 0x5800000
	s_mul_hi_i32 s4, s3, 0x2e8ba2e9
	v_readlane_b32 s6, v242, 2
	s_addc_u32 s1, s5, 0
	s_lshr_b32 s5, s4, 31
	s_ashr_i32 s4, s4, 6
	s_add_i32 s6, s4, s5
	s_mul_i32 s4, s6, 0x160
	s_sub_i32 s4, s3, s4
	s_lshl_b32 s4, s4, 5
	s_ashr_i32 s5, s4, 31
	s_lshl_b64 s[4:5], s[4:5], 2
	s_add_u32 s4, s0, s4
	v_and_b32_e32 v38, 7, v143
	v_lshrrev_b32_e32 v1, 3, v142
	s_addc_u32 s5, s1, s5
	v_lshlrev_b32_e32 v36, 4, v38
	v_mov_b32_e32 v37, 0
	v_readlane_b32 s7, v242, 3
	s_waitcnt vmcnt(0)
	v_lshl_add_u64 v[26:27], s[4:5], 0, v[36:37]
	v_lshl_or_b32 v30, s6, 6, v1
	s_mov_b32 s4, 0xb000
	v_mad_i64_i32 v[2:3], s[6:7], v30, s4, v[26:27]
	v_or_b32_e32 v4, 8, v30
	v_or_b32_e32 v10, 16, v30
	v_or_b32_e32 v12, 24, v30
	v_or_b32_e32 v18, 32, v30
	v_or_b32_e32 v20, 40, v30
	v_or_b32_e32 v28, 48, v30
	v_or_b32_e32 v30, 56, v30
	v_mad_i64_i32 v[6:7], s[6:7], v4, s4, v[26:27]
	v_mad_i64_i32 v[10:11], s[6:7], v10, s4, v[26:27]
	v_mad_i64_i32 v[14:15], s[6:7], v12, s4, v[26:27]
	v_mad_i64_i32 v[18:19], s[6:7], v18, s4, v[26:27]
	v_mad_i64_i32 v[22:23], s[6:7], v20, s4, v[26:27]
	v_mad_i64_i32 v[28:29], s[6:7], v28, s4, v[26:27]
	v_mad_i64_i32 v[30:31], s[6:7], v30, s4, v[26:27]
	global_load_dwordx4 v[2:5], v[2:3], off nt
	s_nop 0
	global_load_dwordx4 v[6:9], v[6:7], off nt
	s_nop 0
	global_load_dwordx4 v[10:13], v[10:11], off nt
	s_nop 0
	global_load_dwordx4 v[14:17], v[14:15], off nt
	s_nop 0
	global_load_dwordx4 v[18:21], v[18:19], off nt
	s_nop 0
	global_load_dwordx4 v[22:25], v[22:23], off nt
	s_nop 0
	global_load_dwordx4 v[26:29], v[28:29], off nt
	s_nop 0
	global_load_dwordx4 v[30:33], v[30:31], off nt
	v_readlane_b32 s5, v242, 29
	v_mul_u32_u24_e32 v38, 0x420, v38
	v_lshlrev_b32_e32 v39, 2, v1
	v_add_u32_e32 v42, s5, v36
	v_mul_u32_u24_e32 v43, 0x84, v1
	v_lshl_add_u64 v[34:35], s[0:1], 0, v[36:37]
	v_lshl_add_u64 v[36:37], s[52:53], 0, v[36:37]
	v_add3_u32 v38, s5, v38, v39
	v_or_b32_e32 v39, 8, v1
	v_or_b32_e32 v40, 16, v1
	v_or_b32_e32 v41, 24, v1
	s_lshl_b32 s5, s3, 5
	v_add_u32_e32 v42, v42, v43
	v_readlane_b32 s10, v242, 6
	v_readlane_b32 s11, v242, 7
	s_branch .LBB0_1044

.LBB0_1044:
	v_add_u32_e32 v43, 0x420, v42
	s_waitcnt vmcnt(7)
	ds_write2_b32 v42, v2, v3 offset1:1
	ds_write2_b32 v42, v4, v5 offset0:2 offset1:3
	s_waitcnt vmcnt(6)
	ds_write2_b32 v43, v6, v7 offset1:1
	v_add_u32_e32 v43, 0x428, v42
	ds_write2_b32 v43, v8, v9 offset1:1
	v_add_u32_e32 v43, 0x840, v42
	s_waitcnt vmcnt(5)
	ds_write2_b32 v43, v10, v11 offset1:1
	v_add_u32_e32 v43, 0x848, v42
	ds_write2_b32 v43, v12, v13 offset1:1
	v_add_u32_e32 v43, 0xc60, v42
	s_waitcnt vmcnt(4)
	ds_write2_b32 v43, v14, v15 offset1:1
	v_add_u32_e32 v43, 0xc68, v42
	ds_write2_b32 v43, v16, v17 offset1:1
	v_add_u32_e32 v43, 0x1080, v42
	s_waitcnt vmcnt(3)
	ds_write2_b32 v43, v18, v19 offset1:1
	v_add_u32_e32 v43, 0x1088, v42
	ds_write2_b32 v43, v20, v21 offset1:1
	v_add_u32_e32 v43, 0x14a0, v42
	s_waitcnt vmcnt(2)
	ds_write2_b32 v43, v22, v23 offset1:1
	v_add_u32_e32 v43, 0x14a8, v42
	ds_write2_b32 v43, v24, v25 offset1:1
	v_add_u32_e32 v43, 0x18c0, v42
	s_add_i32 s6, s3, 0x395
	s_waitcnt vmcnt(1)
	ds_write2_b32 v43, v26, v27 offset1:1
	v_add_u32_e32 v43, 0x18c8, v42
	s_cmpk_gt_i32 s3, 0x286a
	ds_write2_b32 v43, v28, v29 offset1:1
	v_add_u32_e32 v43, 0x1ce0, v42
	s_cselect_b64 s[0:1], -1, 0
	s_waitcnt vmcnt(0)
	ds_write2_b32 v43, v30, v31 offset1:1
	v_add_u32_e32 v43, 0x1ce8, v42
	s_and_b64 vcc, exec, s[0:1]
	ds_write2_b32 v43, v32, v33 offset1:1
	s_cbranch_vccnz .LBB0_1043
	s_mul_hi_i32 s7, s6, 0x2e8ba2e9
	s_lshr_b32 s8, s7, 31
	s_ashr_i32 s7, s7, 6
	s_add_i32 s7, s7, s8
	s_mul_i32 s8, s7, 0xffffd400
	s_add_i32 s8, s5, s8
	s_addk_i32 s8, 0x72a0
	s_ashr_i32 s9, s8, 31
	v_lshl_or_b32 v30, s7, 6, v1
	v_lshl_add_u64 v[26:27], s[8:9], 2, v[34:35]
	v_mad_i64_i32 v[2:3], s[8:9], v30, s4, v[26:27]
	v_or_b32_e32 v4, 8, v30
	v_or_b32_e32 v10, 16, v30
	v_or_b32_e32 v12, 24, v30
	v_or_b32_e32 v18, 32, v30
	v_or_b32_e32 v20, 40, v30
	v_or_b32_e32 v28, 48, v30
	v_or_b32_e32 v30, 56, v30
	v_mad_i64_i32 v[6:7], s[8:9], v4, s4, v[26:27]
	v_mad_i64_i32 v[10:11], s[8:9], v10, s4, v[26:27]
	v_mad_i64_i32 v[14:15], s[8:9], v12, s4, v[26:27]
	v_mad_i64_i32 v[18:19], s[8:9], v18, s4, v[26:27]
	v_mad_i64_i32 v[22:23], s[8:9], v20, s4, v[26:27]
	v_mad_i64_i32 v[28:29], s[8:9], v28, s4, v[26:27]
	v_mad_i64_i32 v[30:31], s[8:9], v30, s4, v[26:27]
	global_load_dwordx4 v[2:5], v[2:3], off nt
	s_nop 0
	global_load_dwordx4 v[6:9], v[6:7], off nt
	s_nop 0
	global_load_dwordx4 v[10:13], v[10:11], off nt
	s_nop 0
	global_load_dwordx4 v[14:17], v[14:15], off nt
	s_nop 0
	global_load_dwordx4 v[18:21], v[18:19], off nt
	s_nop 0
	global_load_dwordx4 v[22:25], v[22:23], off nt
	s_nop 0
	global_load_dwordx4 v[26:29], v[28:29], off nt
	s_nop 0
	global_load_dwordx4 v[30:33], v[30:31], off nt
	s_branch .LBB0_1043

.Lat_pissued:
	v_readlane_b32 s82, v242, 37
	v_readlane_b32 s83, v242, 38
	v_readlane_b32 s84, v242, 39
	v_readlane_b32 s85, v242, 40
	s_mov_b32 s35, s60
	s_and_b32 s86, s35, 3
	s_lshl_b32 s62, s86, 8
	s_lshl_b32 s87, s86, 7
	s_and_b32 s36, s35, -4
	s_add_i32 s36, s36, 0x2000
	s_lshl_b32 s37, s35, 5
	s_and_b32 s37, s37, 0x7fffff80
	v_add_u32_e32 v96, s37, v88
	v_lshlrev_b32_e32 v96, 10, v96
	v_lshl_add_u32 v101, v89, 5, s62
	v_add_u32_e32 v96, v96, v101
	v_add_u32_e32 v97, 0x10000, v96
	v_add_u32_e32 v98, s37, v90
	v_lshlrev_b32_e32 v98, 10, v98
	v_lshl_add_u32 v101, v91, 5, s62
	v_add_u32_e32 v98, v98, v101
	v_add_u32_e32 v99, s36, v88
	v_lshlrev_b32_e32 v99, 9, v99
	v_lshl_add_u32 v101, v89, 4, s87
	v_add_u32_e32 v99, v99, v101
	v_add_u32_e32 v100, s36, v95
	v_lshlrev_b32_e32 v100, 9, v100
	v_lshl_add_u32 v101, v91, 4, s87
	v_add_u32_e32 v100, v100, v101
	v_mov_b32_e32 v176, 0
	v_mov_b32_e32 v177, 0
	v_mov_b32_e32 v178, 0
	v_mov_b32_e32 v179, 0
	v_mov_b32_e32 v180, 0
	v_mov_b32_e32 v181, 0
	v_mov_b32_e32 v182, 0
	v_mov_b32_e32 v183, 0
	v_mov_b32_e32 v188, 0
	v_mov_b32_e32 v189, 0
	v_mov_b32_e32 v190, 0
	v_mov_b32_e32 v191, 0
	v_mov_b32_e32 v196, 0
	v_mov_b32_e32 v197, 0
	v_mov_b32_e32 v198, 0
	v_mov_b32_e32 v199, 0
	v_mov_b32_e32 v204, 0
	v_mov_b32_e32 v205, 0
	v_mov_b32_e32 v206, 0
	v_mov_b32_e32 v207, 0
	global_load_dwordx4 v[160:163], v96, s[82:83] nt
	global_load_dwordx4 v[164:167], v96, s[82:83] offset:16 nt
	global_load_dwordx4 v[168:171], v97, s[82:83] nt
	global_load_dwordx4 v[172:175], v97, s[82:83] offset:16 nt
	v_cmp_gt_u32_e32 vcc, 0x80, v90
	s_and_saveexec_b64 s[90:91], vcc
	global_load_dwordx4 v[180:183], v98, s[84:85] offset:0 nt
	global_load_dwordx4 v[184:187], v98, s[84:85] offset:16 nt
	global_load_dwordx4 v[188:191], v98, s[84:85] offset:64 nt
	global_load_dwordx4 v[192:195], v98, s[84:85] offset:80 nt
	global_load_dwordx4 v[196:199], v98, s[84:85] offset:128 nt
	global_load_dwordx4 v[200:203], v98, s[84:85] offset:144 nt
	global_load_dwordx4 v[204:207], v98, s[84:85] offset:192 nt
	global_load_dwordx4 v[208:211], v98, s[84:85] offset:208 nt
	s_mov_b64 exec, s[90:91]
	v_cmp_gt_u32_e32 vcc, 32, v143
	s_and_saveexec_b64 s[90:91], vcc
	global_load_dwordx4 v[176:179], v99, s[48:49]
	s_mov_b64 exec, s[90:91]
	v_cmp_gt_u32_e32 vcc, 4, v95
	s_and_saveexec_b64 s[90:91], vcc
	global_load_dwordx4 v[180:183], v100, s[54:55] offset:0
	global_load_dwordx4 v[188:191], v100, s[54:55] offset:32
	global_load_dwordx4 v[196:199], v100, s[54:55] offset:64
	global_load_dwordx4 v[204:207], v100, s[54:55] offset:96
	s_mov_b64 exec, s[90:91]
	s_add_i32 s35, s60, 0x100
	s_and_b32 s86, s35, 3
	s_lshl_b32 s62, s86, 8
	s_lshl_b32 s87, s86, 7
	s_and_b32 s36, s35, -4
	s_add_i32 s36, s36, 0x2000
	s_lshl_b32 s37, s35, 5
	s_and_b32 s37, s37, 0x7fffff80
	v_add_u32_e32 v96, s37, v88
	v_lshlrev_b32_e32 v96, 10, v96
	v_lshl_add_u32 v101, v89, 5, s62
	v_add_u32_e32 v96, v96, v101
	v_add_u32_e32 v97, 0x10000, v96
	v_add_u32_e32 v98, s37, v90
	v_lshlrev_b32_e32 v98, 10, v98
	v_lshl_add_u32 v101, v91, 5, s62
	v_add_u32_e32 v98, v98, v101
	v_add_u32_e32 v99, s36, v88
	v_lshlrev_b32_e32 v99, 9, v99
	v_lshl_add_u32 v101, v89, 4, s87
	v_add_u32_e32 v99, v99, v101
	v_add_u32_e32 v100, s36, v95
	v_lshlrev_b32_e32 v100, 9, v100
	v_lshl_add_u32 v101, v91, 4, s87
	v_add_u32_e32 v100, v100, v101
	v_mov_b32_e32 v132, 0
	v_mov_b32_e32 v133, 0
	v_mov_b32_e32 v134, 0
	v_mov_b32_e32 v135, 0
	v_mov_b32_e32 v136, 0
	v_mov_b32_e32 v137, 0
	v_mov_b32_e32 v138, 0
	v_mov_b32_e32 v139, 0
	v_mov_b32_e32 v216, 0
	v_mov_b32_e32 v217, 0
	v_mov_b32_e32 v218, 0
	v_mov_b32_e32 v219, 0
	v_mov_b32_e32 v224, 0
	v_mov_b32_e32 v225, 0
	v_mov_b32_e32 v226, 0
	v_mov_b32_e32 v227, 0
	v_mov_b32_e32 v232, 0
	v_mov_b32_e32 v233, 0
	v_mov_b32_e32 v234, 0
	v_mov_b32_e32 v235, 0
	global_load_dwordx4 v[116:119], v96, s[82:83] nt
	global_load_dwordx4 v[120:123], v96, s[82:83] offset:16 nt
	global_load_dwordx4 v[124:127], v97, s[82:83] nt
	global_load_dwordx4 v[128:131], v97, s[82:83] offset:16 nt
	v_cmp_gt_u32_e32 vcc, 0x80, v90
	s_and_saveexec_b64 s[90:91], vcc
	global_load_dwordx4 v[136:139], v98, s[84:85] offset:0 nt
	global_load_dwordx4 v[212:215], v98, s[84:85] offset:16 nt
	global_load_dwordx4 v[216:219], v98, s[84:85] offset:64 nt
	global_load_dwordx4 v[220:223], v98, s[84:85] offset:80 nt
	global_load_dwordx4 v[224:227], v98, s[84:85] offset:128 nt
	global_load_dwordx4 v[228:231], v98, s[84:85] offset:144 nt
	global_load_dwordx4 v[232:235], v98, s[84:85] offset:192 nt
	global_load_dwordx4 v[236:239], v98, s[84:85] offset:208 nt
	s_mov_b64 exec, s[90:91]
	v_cmp_gt_u32_e32 vcc, 32, v143
	s_and_saveexec_b64 s[90:91], vcc
	global_load_dwordx4 v[132:135], v99, s[48:49]
	s_mov_b64 exec, s[90:91]
	v_cmp_gt_u32_e32 vcc, 4, v95
	s_and_saveexec_b64 s[90:91], vcc
	global_load_dwordx4 v[136:139], v100, s[54:55] offset:0
	global_load_dwordx4 v[216:219], v100, s[54:55] offset:32
	global_load_dwordx4 v[224:227], v100, s[54:55] offset:64
	global_load_dwordx4 v[232:235], v100, s[54:55] offset:96
	s_mov_b64 exec, s[90:91]
	s_waitcnt vmcnt(0)
	ds_write_b128 v92, v[56:59]
	ds_write_b128 v92, v[60:63] offset:9216
	ds_write_b128 v92, v[64:67] offset:18432
	ds_write_b128 v92, v[68:71] offset:27648
	ds_write_b16 v93, v72 offset:36864
	ds_write_b16_d16_hi v93, v72 offset:37392
	ds_write_b16 v93, v73 offset:37920
	ds_write_b16_d16_hi v93, v73 offset:38448
	ds_write_b16 v93, v74 offset:38976
	ds_write_b16_d16_hi v93, v74 offset:39504
	ds_write_b16 v93, v75 offset:40032
	ds_write_b16_d16_hi v93, v75 offset:40560
	ds_write_b16 v93, v76 offset:45312
	ds_write_b16_d16_hi v93, v76 offset:45840
	ds_write_b16 v93, v77 offset:46368
	ds_write_b16_d16_hi v93, v77 offset:46896
	ds_write_b16 v93, v78 offset:47424
	ds_write_b16_d16_hi v93, v78 offset:47952
	ds_write_b16 v93, v79 offset:48480
	ds_write_b16_d16_hi v93, v79 offset:49008
	ds_write_b16 v94, v80 offset:36864
	ds_write_b16_d16_hi v94, v80 offset:37392
	ds_write_b16 v94, v81 offset:37920
	ds_write_b16_d16_hi v94, v81 offset:38448
	ds_write_b16 v94, v82 offset:38976
	ds_write_b16_d16_hi v94, v82 offset:39504
	ds_write_b16 v94, v83 offset:40032
	ds_write_b16_d16_hi v94, v83 offset:40560
	ds_write_b16 v94, v84 offset:45312
	ds_write_b16_d16_hi v94, v84 offset:45840
	ds_write_b16 v94, v85 offset:46368
	ds_write_b16_d16_hi v94, v85 offset:46896
	ds_write_b16 v94, v86 offset:47424
	ds_write_b16_d16_hi v94, v86 offset:47952
	ds_write_b16 v94, v87 offset:48480
	ds_write_b16_d16_hi v94, v87 offset:49008
	s_mov_b32 s66, 0
	s_lshl_b32 s34, s67, 2
	v_readlane_b32 s80, v242, 0
	v_mov_b32_e32 v2, s34
	v_readlane_b32 s81, v242, 1
	s_waitcnt lgkmcnt(0)
	s_barrier
	v_and_b32_e32 v3, 64, v53
	v_add_u32_e32 v3, 64, v3
	s_nop 0
	global_load_dword v37, v2, s[80:81]
	v_xor_b32_e32 v2, 16, v53
	v_cmp_lt_i32_e32 vcc, v2, v3
	s_and_b32 s36, s59, 15
	s_lshl_b32 s34, s67, 6
	v_cndmask_b32_e32 v2, v53, v2, vcc
	v_lshlrev_b32_e32 v55, 2, v2
	v_xor_b32_e32 v2, 32, v53
	v_cmp_lt_i32_e32 vcc, v2, v3
	s_and_b32 s35, s42, 0xfffff800
	s_lshl_b32 s36, s36, 7
	v_cndmask_b32_e32 v2, v53, v2, vcc
	s_or_b32 s35, s35, s36
	v_lshlrev_b32_e32 v56, 2, v2
	s_lshl_b32 s62, s34, 1
	v_mov_b64_e32 v[2:3], v[10:11]
	v_mov_b64_e32 v[6:7], v[14:15]
	v_lshl_add_u64 v[38:39], v[34:35], 0, s[62:63]
	v_or_b32_e32 v57, s35, v1
	s_mov_b32 s34, 0
	v_mov_b64_e32 v[4:5], v[12:13]
	v_mov_b64_e32 v[8:9], v[16:17]
	v_readlane_b32 s82, v242, 2
	v_readlane_b32 s83, v242, 3
	v_readlane_b32 s84, v242, 4
	v_readlane_b32 s85, v242, 5
	v_readlane_b32 s86, v242, 6
	v_readlane_b32 s87, v242, 7
	s_branch .LBB0_1177

.LBB0_1346:
	s_cmp_lt_i32 s72, 13
	s_cselect_b64 s[4:5], -1, 0
	s_and_b64 s[0:1], s[4:5], s[0:1]
	s_andn2_b64 vcc, exec, s[0:1]
	s_cbranch_vccnz .LBB0_1353
	v_readlane_b32 s4, v242, 55
	s_cmpk_gt_i32 s4, 0x21ff
	v_readlane_b32 s5, v242, 56
	s_cbranch_scc1 .LBB0_1353
	v_readlane_b32 s4, v242, 31
	v_readlane_b32 s12, v242, 39
	v_readlane_b32 s13, v242, 40
	v_readlane_b32 s14, v242, 41
	v_readlane_b32 s15, v242, 42
	v_readlane_b32 s16, v242, 43
	v_readlane_b32 s17, v242, 44
	s_waitcnt vmcnt(0)
	v_lshlrev_b32_e32 v66, 4, v142
	v_mov_b32_e32 v67, 0
	v_readlane_b32 s18, v242, 45
	v_readlane_b32 s19, v242, 46
	s_mov_b64 s[12:13], s[16:17]
	v_lshl_add_u64 v[34:35], s[12:13], 0, v[66:67]
	s_mov_b64 s[14:15], s[18:19]
	v_add_co_u32_e32 v2, vcc, 0x2000, v34
	v_readlane_b32 s10, v242, 37
	v_readlane_b32 s11, v242, 38
	v_lshl_add_u64 v[38:39], s[14:15], 0, v[66:67]
	v_addc_co_u32_e32 v3, vcc, 0, v35, vcc
	v_readlane_b32 s5, v242, 32
	v_add_co_u32_e32 v42, vcc, 0x2000, v38
	v_readlane_b32 s10, v242, 55
	s_mov_b64 s[4:5], 0x2000
	v_addc_co_u32_e32 v43, vcc, 0, v39, vcc
	v_readlane_b32 s11, v242, 56
	v_readlane_b32 s6, v242, 33
	v_readlane_b32 s7, v242, 34
	v_lshl_add_u64 v[36:37], v[34:35], 0, s[4:5]
	v_lshl_add_u64 v[40:41], v[38:39], 0, s[4:5]
	global_load_dwordx4 v[2:5], v[2:3], off
	s_nop 0
	global_load_dwordx4 v[6:9], v[42:43], off
	global_load_dwordx4 v[10:13], v[36:37], off offset:1024
	global_load_dwordx4 v[14:17], v[36:37], off offset:2048
	global_load_dwordx4 v[18:21], v[40:41], off offset:1024
	global_load_dwordx4 v[22:25], v[40:41], off offset:2048
	global_load_dwordx4 v[26:29], v[36:37], off offset:3072
	global_load_dwordx4 v[30:33], v[40:41], off offset:3072
	v_add_co_u32_e32 v58, vcc, 0x3000, v34
	s_ashr_i32 s11, s10, 31
	s_nop 0
	v_addc_co_u32_e32 v59, vcc, 0, v35, vcc
	s_lshl_b64 s[4:5], s[10:11], 12
	v_readlane_b32 s6, v242, 51
	v_add_co_u32_e32 v68, vcc, 0x3000, v38
	v_readlane_b32 s7, v242, 52
	s_add_u32 s6, s6, s4
	v_readlane_b32 s8, v242, 35
	v_addc_co_u32_e32 v69, vcc, 0, v39, vcc
	global_load_dwordx4 v[34:37], v[58:59], off
	global_load_dwordx4 v[38:41], v[58:59], off offset:1024
	global_load_dwordx4 v[42:45], v[68:69], off
	global_load_dwordx4 v[46:49], v[68:69], off offset:1024
	s_addc_u32 s7, s7, s5
	v_readlane_b32 s9, v242, 36
	s_add_u32 s8, s40, s4
	v_lshlrev_b32_e32 v66, 3, v142
	s_addc_u32 s9, s41, s5
	s_nop 1
	global_load_dwordx2 v[120:121], v66, s[8:9] offset:2048 nt
	global_load_dwordx2 v[118:119], v66, s[8:9] offset:2560 nt
	global_load_dwordx2 v[116:117], v66, s[8:9] offset:3072 nt
	global_load_dwordx2 v[114:115], v66, s[8:9] offset:3584 nt
	global_load_dwordx2 v[128:129], v66, s[8:9] nt
	global_load_dwordx2 v[126:127], v66, s[8:9] offset:512 nt
	global_load_dwordx2 v[124:125], v66, s[8:9] offset:1024 nt
	global_load_dwordx2 v[122:123], v66, s[8:9] offset:1536 nt
	global_load_dwordx4 v[50:53], v[58:59], off offset:2048
	s_waitcnt lgkmcnt(0)
	global_load_dwordx4 v[54:57], v[58:59], off offset:3072
	global_load_dwordx2 v[130:131], v66, s[6:7] nt
	global_load_dwordx2 v[112:113], v66, s[6:7] offset:512 nt
	global_load_dwordx2 v[110:111], v66, s[6:7] offset:1024 nt
	global_load_dwordx2 v[108:109], v66, s[6:7] offset:1536 nt
	global_load_dwordx2 v[106:107], v66, s[6:7] offset:2048 nt
	global_load_dwordx2 v[104:105], v66, s[6:7] offset:2560 nt
	global_load_dwordx2 v[102:103], v66, s[6:7] offset:3072 nt
	global_load_dwordx2 v[100:101], v66, s[6:7] offset:3584 nt
	global_load_dwordx4 v[58:61], v[68:69], off offset:2048
	global_load_dwordx4 v[62:65], v[68:69], off offset:3072
	v_mbcnt_lo_u32_b32 v1, -1, 0
	v_mbcnt_hi_u32_b32 v68, -1, v1
	v_and_b32_e32 v1, 64, v68
	v_add_u32_e32 v69, 64, v1
	v_xor_b32_e32 v1, 1, v68
	v_cmp_lt_i32_e32 vcc, v1, v69
	v_xor_b32_e32 v70, 2, v68
	s_add_u32 s4, s70, s4
	v_cndmask_b32_e32 v1, v68, v1, vcc
	v_cmp_lt_i32_e32 vcc, v70, v69
	s_addc_u32 s5, s71, s5
	s_add_i32 s8, s10, s64
	v_cndmask_b32_e32 v70, v68, v70, vcc
	v_lshlrev_b32_e32 v132, 2, v70
	v_xor_b32_e32 v70, 4, v68
	v_cmp_lt_i32_e32 vcc, v70, v69
	s_ashr_i32 s65, s64, 31
	s_ashr_i32 s9, s8, 31
	v_cndmask_b32_e32 v70, v68, v70, vcc
	v_lshlrev_b32_e32 v133, 2, v70
	v_xor_b32_e32 v70, 8, v68
	v_cmp_lt_i32_e32 vcc, v70, v69
	s_lshl_b64 s[6:7], s[64:65], 12
	s_lshl_b64 s[8:9], s[8:9], 12
	v_cndmask_b32_e32 v70, v68, v70, vcc
	v_lshlrev_b32_e32 v134, 2, v70
	v_xor_b32_e32 v70, 16, v68
	v_cmp_lt_i32_e32 vcc, v70, v69
	s_mov_b32 s14, s10
	s_add_u32 s8, s70, s8
	v_cndmask_b32_e32 v70, v68, v70, vcc
	v_lshlrev_b32_e32 v135, 2, v70
	v_xor_b32_e32 v70, 32, v68
	v_cmp_lt_i32_e32 vcc, v70, v69
	v_writelane_b32 v242, s14, 55
	v_lshlrev_b32_e32 v1, 2, v1
	v_cndmask_b32_e32 v68, v68, v70, vcc
	v_lshlrev_b32_e32 v136, 2, v68
	s_addc_u32 s9, s71, s9
	s_mov_b32 s3, 0x1d000000
	v_mov_b32_e32 v137, 0x358637bd
	s_mov_b32 s12, 0x800000
	s_brev_b32 s13, 48
	v_writelane_b32 v242, s15, 56
	s_mov_b32 s14, s10
	s_waitcnt vmcnt(19)
	v_mov_b64_e32 v[88:89], v[120:121]
	s_waitcnt vmcnt(18)
	v_mov_b64_e32 v[86:87], v[118:119]
	s_waitcnt vmcnt(17)
	v_mov_b64_e32 v[84:85], v[116:117]
	s_waitcnt vmcnt(16)
	v_mov_b64_e32 v[82:83], v[114:115]
	s_waitcnt vmcnt(15)
	v_mov_b64_e32 v[96:97], v[128:129]
	s_waitcnt vmcnt(14)
	v_mov_b64_e32 v[94:95], v[126:127]
	s_waitcnt vmcnt(13)
	v_mov_b64_e32 v[92:93], v[124:125]
	s_waitcnt vmcnt(12)
	v_mov_b64_e32 v[90:91], v[122:123]
	s_waitcnt vmcnt(9)
	v_mov_b64_e32 v[68:69], v[130:131]
	s_waitcnt vmcnt(8)
	v_mov_b64_e32 v[70:71], v[112:113]
	s_waitcnt vmcnt(7)
	v_mov_b64_e32 v[72:73], v[110:111]
	s_waitcnt vmcnt(6)
	v_mov_b64_e32 v[74:75], v[108:109]
	s_waitcnt vmcnt(5)
	v_mov_b64_e32 v[76:77], v[106:107]
	s_waitcnt vmcnt(4)
	v_mov_b64_e32 v[78:79], v[104:105]
	s_waitcnt vmcnt(3)
	v_mov_b64_e32 v[80:81], v[102:103]
	s_waitcnt vmcnt(2)
	v_mov_b64_e32 v[98:99], v[100:101]
	s_branch .LBB0_1350

.LBB0_1350:
	s_add_i32 s14, s14, s64
	s_cmpk_gt_i32 s14, 0x21ff
	s_cselect_b64 s[10:11], -1, 0
	s_and_b64 vcc, exec, s[10:11]
	s_cbranch_vccnz .LBB0_1349
	v_lshl_add_u64 v[82:83], s[8:9], 0, v[66:67]
	v_add_co_u32_e32 v84, vcc, 0x1d000000, v82
	s_nop 1
	v_addc_co_u32_e32 v85, vcc, 0, v83, vcc
	v_add_co_u32_e32 v82, vcc, 0xe200000, v82
	global_load_dwordx2 v[68:69], v[84:85], off nt
	global_load_dwordx2 v[70:71], v[84:85], off offset:512 nt
	global_load_dwordx2 v[72:73], v[84:85], off offset:1024 nt
	global_load_dwordx2 v[74:75], v[84:85], off offset:1536 nt
	global_load_dwordx2 v[76:77], v[84:85], off offset:2048 nt
	global_load_dwordx2 v[78:79], v[84:85], off offset:2560 nt
	global_load_dwordx2 v[80:81], v[84:85], off offset:3072 nt
	global_load_dwordx2 v[98:99], v[84:85], off offset:3584 nt
	v_addc_co_u32_e32 v83, vcc, 0, v83, vcc
	global_load_dwordx2 v[96:97], v[82:83], off nt
	global_load_dwordx2 v[94:95], v[82:83], off offset:512 nt
	global_load_dwordx2 v[92:93], v[82:83], off offset:1024 nt
	global_load_dwordx2 v[90:91], v[82:83], off offset:1536 nt
	global_load_dwordx2 v[88:89], v[82:83], off offset:2048 nt
	global_load_dwordx2 v[86:87], v[82:83], off offset:2560 nt
	global_load_dwordx2 v[84:85], v[82:83], off offset:3072 nt
	s_nop 0
	global_load_dwordx2 v[82:83], v[82:83], off offset:3584 nt
	s_branch .LBB0_1349
